# stack_plus_first_iteration_peel_srcC0_all_gemm_loops
# speedup vs baseline: 1.0110x; 1.0024x over previous
.LBB0_215:
	s_ashr_i32 s45, s44, 31
	s_lshl_b64 s[46:47], s[44:45], 19
	s_add_u32 s46, s60, s46
	s_addc_u32 s47, s61, s47
	s_and_b64 s[48:49], s[12:13], exec
	s_cselect_b32 s58, s47, s15
	s_cselect_b32 s59, s46, s14
	s_ashr_i32 s43, s42, 31
	s_lshl_b64 s[48:49], s[42:43], 19
	s_add_u32 s48, s63, s48
	s_addc_u32 s49, s64, s49
	s_and_b64 s[52:53], s[12:13], exec
	s_cselect_b32 s43, s49, s51
	s_cselect_b32 s77, s48, s50
	s_lshl_b64 s[52:53], s[44:45], 10
	s_add_u32 s45, s33, s52
	s_addc_u32 s78, s62, s53
	s_add_u32 s79, s50, 0x100
	s_addc_u32 s80, s51, 0
	s_mov_b32 s81, -2
	s_cmp_eq_u32 s81, 12
	s_cselect_b64 s[52:53], -1, 0
	s_and_b64 s[50:51], s[12:13], s[52:53]
	s_andn2_b64 vcc, exec, s[50:51]
	s_cbranch_vccnz .Lpeel216_220
	v_mov_b32_e32 v0, v165
	s_nop 0
	v_readfirstlane_b32 s50, v0
	s_ashr_i32 s51, s50, 6
	s_cmp_gt_i32 s51, 3
	s_cbranch_scc1 .Lpeel216_219
	s_and_b64 s[54:55], s[38:39], exec
	s_cselect_b32 s54, 0x1400, 0
	s_add_i32 s54, s54, 0
	s_lshl_b32 s51, s51, 8
	s_add_i32 s51, s54, s51
	s_andn2_b32 s50, s50, 63
	s_add_i32 m0, s51, 0x20400
	s_ashr_i32 s51, s50, 31
	s_lshl_b64 s[50:51], s[50:51], 2
	s_add_u32 s50, s45, s50
	v_and_b32_e32 v0, 63, v0
	s_addc_u32 s51, s78, s51
	v_lshlrev_b32_e32 v0, 2, v0
	global_load_lds_dword v0, s[50:51]

.Lpeel216_220:
	s_add_u32 s50, s14, 0x100
	s_addc_u32 s51, s15, 0
	s_and_b64 s[52:53], s[52:53], exec
	s_cselect_b32 s55, s58, s51
	s_cselect_b32 s54, s59, s50
	s_cselect_b32 s53, s43, s80
	s_cselect_b32 s52, s77, s79
	s_add_i32 s82, 0, 0x10000
	v_add_u32_e32 v0, s82, v187
	s_add_i32 s83, 0, 0x14000
	ds_read_b128 v[130:133], v0
	ds_read_b128 v[134:137], v0 offset:1024
	ds_read_b128 v[176:179], v0 offset:2048
	ds_read_b128 v[180:183], v0 offset:3072
	v_add_u32_e32 v0, s83, v187
	ds_read_b128 v[192:195], v0
	ds_read_b128 v[196:199], v0 offset:1024
	ds_read_b128 v[200:203], v0 offset:2048
	ds_read_b128 v[204:207], v0 offset:3072
	v_lshl_add_u64 v[184:185], s[14:15], 0, v[172:173]
	s_add_i32 m0, s66, 0xc000
	ds_read_b128 v[208:211], v190
	ds_read_b128 v[212:215], v190 offset:1024
	ds_read_b128 v[226:229], v190 offset:2048
	ds_read_b128 v[230:233], v190 offset:3072
	ds_read_b128 v[234:237], v190 offset:4096
	ds_read_b128 v[238:241], v190 offset:5120
	ds_read_b128 v[242:245], v190 offset:6144
	ds_read_b128 v[246:249], v190 offset:7168
	global_load_lds_dwordx4 v[184:185], off
	v_lshl_add_u64 v[184:185], s[14:15], 0, v[174:175]
	s_add_i32 m0, s66, 0xe000
	s_nop 0
	global_load_lds_dwordx4 v[184:185], off
	s_waitcnt vmcnt(8)
	s_waitcnt lgkmcnt(0)
	s_barrier
	s_setprio 1
	v_mfma_f32_16x16x32_bf16 v[126:129], v[130:133], v[208:211], 0
	v_mfma_f32_16x16x32_bf16 v[122:125], v[176:179], v[208:211], 0
	v_mfma_f32_16x16x32_bf16 v[110:113], v[130:133], v[226:229], 0
	v_mfma_f32_16x16x32_bf16 v[106:109], v[176:179], v[226:229], 0
	v_mfma_f32_16x16x32_bf16 v[94:97], v[130:133], v[234:237], 0
	v_mfma_f32_16x16x32_bf16 v[90:93], v[176:179], v[234:237], 0
	v_mfma_f32_16x16x32_bf16 v[78:81], v[130:133], v[242:245], 0
	v_mfma_f32_16x16x32_bf16 v[74:77], v[176:179], v[242:245], 0
	v_mfma_f32_16x16x32_bf16 v[126:129], v[134:137], v[212:215], v[126:129]
	v_mfma_f32_16x16x32_bf16 v[122:125], v[180:183], v[212:215], v[122:125]
	v_mfma_f32_16x16x32_bf16 v[110:113], v[134:137], v[230:233], v[110:113]
	v_mfma_f32_16x16x32_bf16 v[106:109], v[180:183], v[230:233], v[106:109]
	v_mfma_f32_16x16x32_bf16 v[94:97], v[134:137], v[238:241], v[94:97]
	v_mfma_f32_16x16x32_bf16 v[90:93], v[180:183], v[238:241], v[90:93]
	v_mfma_f32_16x16x32_bf16 v[78:81], v[134:137], v[246:249], v[78:81]
	v_mfma_f32_16x16x32_bf16 v[74:77], v[180:183], v[246:249], v[74:77]
	s_setprio 0
	s_setprio 1
	v_mfma_f32_16x16x32_bf16 v[118:121], v[192:195], v[208:211], 0
	v_mfma_f32_16x16x32_bf16 v[114:117], v[200:203], v[208:211], 0
	v_mfma_f32_16x16x32_bf16 v[102:105], v[192:195], v[226:229], 0
	v_mfma_f32_16x16x32_bf16 v[98:101], v[200:203], v[226:229], 0
	v_mfma_f32_16x16x32_bf16 v[86:89], v[192:195], v[234:237], 0
	v_mfma_f32_16x16x32_bf16 v[82:85], v[200:203], v[234:237], 0
	v_mfma_f32_16x16x32_bf16 v[70:73], v[192:195], v[242:245], 0
	v_mfma_f32_16x16x32_bf16 v[66:69], v[200:203], v[242:245], 0
	v_mfma_f32_16x16x32_bf16 v[118:121], v[196:199], v[212:215], v[118:121]
	v_mfma_f32_16x16x32_bf16 v[114:117], v[204:207], v[212:215], v[114:117]
	v_mfma_f32_16x16x32_bf16 v[102:105], v[196:199], v[230:233], v[102:105]
	v_mfma_f32_16x16x32_bf16 v[98:101], v[204:207], v[230:233], v[98:101]
	v_mfma_f32_16x16x32_bf16 v[86:89], v[196:199], v[238:241], v[86:89]
	v_mfma_f32_16x16x32_bf16 v[82:85], v[204:207], v[238:241], v[82:85]
	v_mfma_f32_16x16x32_bf16 v[70:73], v[196:199], v[246:249], v[70:73]
	v_mfma_f32_16x16x32_bf16 v[66:69], v[204:207], v[246:249], v[66:69]
	s_setprio 0
	s_barrier
	s_add_i32 s14, s82, s65
	v_lshl_add_u64 v[184:185], s[52:53], 0, v[140:141]
	s_mov_b32 m0, s14
	ds_read_b128 v[208:211], v190 offset:16384
	ds_read_b128 v[212:215], v190 offset:17408
	ds_read_b128 v[226:229], v190 offset:18432
	ds_read_b128 v[230:233], v190 offset:19456
	ds_read_b128 v[234:237], v190 offset:20480
	ds_read_b128 v[238:241], v190 offset:21504
	ds_read_b128 v[242:245], v190 offset:22528
	ds_read_b128 v[246:249], v190 offset:23552
	global_load_lds_dwordx4 v[184:185], off
	s_add_i32 m0, s14, 0x2000
	s_add_u32 s14, s52, 0x40000
	v_lshl_add_u64 v[216:217], s[52:53], 0, v[144:145]
	s_addc_u32 s15, s53, 0
	s_add_i32 s82, s83, s65
	global_load_lds_dwordx4 v[216:217], off
	v_lshl_add_u64 v[218:219], s[14:15], 0, v[140:141]
	s_mov_b32 m0, s82
	v_lshl_add_u64 v[220:221], s[54:55], 0, v[142:143]
	global_load_lds_dwordx4 v[218:219], off
	v_lshl_add_u64 v[218:219], s[14:15], 0, v[144:145]
	s_add_i32 m0, s82, 0x2000
	s_nop 0
	global_load_lds_dwordx4 v[218:219], off
	v_lshl_add_u64 v[218:219], s[54:55], 0, v[138:139]
	s_mov_b32 m0, s66
	s_nop 0
	global_load_lds_dwordx4 v[218:219], off
	s_mov_b32 m0, s67
	s_nop 0
	global_load_lds_dwordx4 v[220:221], off
	s_waitcnt vmcnt(8)
	s_waitcnt lgkmcnt(0)
	s_barrier
	s_setprio 1
	v_mfma_f32_16x16x32_bf16 v[62:65], v[130:133], v[208:211], 0
	v_mfma_f32_16x16x32_bf16 v[58:61], v[176:179], v[208:211], 0
	v_mfma_f32_16x16x32_bf16 v[46:49], v[130:133], v[226:229], 0
	v_mfma_f32_16x16x32_bf16 v[42:45], v[176:179], v[226:229], 0
	v_mfma_f32_16x16x32_bf16 v[30:33], v[130:133], v[234:237], 0
	v_mfma_f32_16x16x32_bf16 v[26:29], v[176:179], v[234:237], 0
	v_mfma_f32_16x16x32_bf16 v[14:17], v[130:133], v[242:245], 0
	v_mfma_f32_16x16x32_bf16 v[10:13], v[176:179], v[242:245], 0
	v_mfma_f32_16x16x32_bf16 v[62:65], v[134:137], v[212:215], v[62:65]
	v_mfma_f32_16x16x32_bf16 v[58:61], v[180:183], v[212:215], v[58:61]
	v_mfma_f32_16x16x32_bf16 v[46:49], v[134:137], v[230:233], v[46:49]
	v_mfma_f32_16x16x32_bf16 v[42:45], v[180:183], v[230:233], v[42:45]
	v_mfma_f32_16x16x32_bf16 v[30:33], v[134:137], v[238:241], v[30:33]
	v_mfma_f32_16x16x32_bf16 v[26:29], v[180:183], v[238:241], v[26:29]
	v_mfma_f32_16x16x32_bf16 v[14:17], v[134:137], v[246:249], v[14:17]
	v_mfma_f32_16x16x32_bf16 v[10:13], v[180:183], v[246:249], v[10:13]
	s_setprio 0
	s_setprio 1
	v_mfma_f32_16x16x32_bf16 v[54:57], v[192:195], v[208:211], 0
	v_mfma_f32_16x16x32_bf16 v[50:53], v[200:203], v[208:211], 0
	v_mfma_f32_16x16x32_bf16 v[38:41], v[192:195], v[226:229], 0
	v_mfma_f32_16x16x32_bf16 v[34:37], v[200:203], v[226:229], 0
	v_mfma_f32_16x16x32_bf16 v[22:25], v[192:195], v[234:237], 0
	v_mfma_f32_16x16x32_bf16 v[18:21], v[200:203], v[234:237], 0
	v_mfma_f32_16x16x32_bf16 v[6:9], v[192:195], v[242:245], 0
	v_mfma_f32_16x16x32_bf16 v[2:5], v[200:203], v[242:245], 0
	v_mfma_f32_16x16x32_bf16 v[54:57], v[196:199], v[212:215], v[54:57]
	v_mfma_f32_16x16x32_bf16 v[50:53], v[204:207], v[212:215], v[50:53]
	v_mfma_f32_16x16x32_bf16 v[38:41], v[196:199], v[230:233], v[38:41]
	v_mfma_f32_16x16x32_bf16 v[34:37], v[204:207], v[230:233], v[34:37]
	v_mfma_f32_16x16x32_bf16 v[22:25], v[196:199], v[238:241], v[22:25]
	v_mfma_f32_16x16x32_bf16 v[18:21], v[204:207], v[238:241], v[18:21]
	v_mfma_f32_16x16x32_bf16 v[6:9], v[196:199], v[246:249], v[6:9]
	v_mfma_f32_16x16x32_bf16 v[2:5], v[204:207], v[246:249], v[2:5]
	s_setprio 0
	s_barrier
	s_add_i32 s82, 0, 0x18000
	v_add_u32_e32 v0, s82, v187
	s_add_i32 s83, 0, 0x1c000
	ds_read_b128 v[130:133], v0
	ds_read_b128 v[134:137], v0 offset:1024
	ds_read_b128 v[176:179], v0 offset:2048
	ds_read_b128 v[180:183], v0 offset:3072
	v_add_u32_e32 v0, s83, v187
	ds_read_b128 v[192:195], v0
	ds_read_b128 v[196:199], v0 offset:1024
	ds_read_b128 v[200:203], v0 offset:2048
	ds_read_b128 v[204:207], v0 offset:3072
	s_add_u32 s14, s54, 0x40000
	s_addc_u32 s15, s55, 0
	s_mov_b32 m0, s68
	v_lshl_add_u64 v[250:251], s[14:15], 0, v[138:139]
	ds_read_b128 v[208:211], v190 offset:32768
	ds_read_b128 v[212:215], v190 offset:33792
	ds_read_b128 v[226:229], v190 offset:34816
	ds_read_b128 v[230:233], v190 offset:35840
	ds_read_b128 v[234:237], v190 offset:36864
	ds_read_b128 v[238:241], v190 offset:37888
	ds_read_b128 v[242:245], v190 offset:38912
	ds_read_b128 v[246:249], v190 offset:39936
	global_load_lds_dwordx4 v[250:251], off
	v_lshl_add_u64 v[250:251], s[14:15], 0, v[142:143]
	s_mov_b32 m0, s69
	s_nop 0
	global_load_lds_dwordx4 v[250:251], off
	s_waitcnt vmcnt(8)
	s_waitcnt lgkmcnt(0)
	s_barrier
	s_setprio 1
	v_mfma_f32_16x16x32_bf16 v[126:129], v[130:133], v[208:211], v[126:129]
	v_mfma_f32_16x16x32_bf16 v[122:125], v[176:179], v[208:211], v[122:125]
	v_mfma_f32_16x16x32_bf16 v[110:113], v[130:133], v[226:229], v[110:113]
	v_mfma_f32_16x16x32_bf16 v[106:109], v[176:179], v[226:229], v[106:109]
	v_mfma_f32_16x16x32_bf16 v[94:97], v[130:133], v[234:237], v[94:97]
	v_mfma_f32_16x16x32_bf16 v[90:93], v[176:179], v[234:237], v[90:93]
	v_mfma_f32_16x16x32_bf16 v[78:81], v[130:133], v[242:245], v[78:81]
	v_mfma_f32_16x16x32_bf16 v[74:77], v[176:179], v[242:245], v[74:77]
	v_mfma_f32_16x16x32_bf16 v[126:129], v[134:137], v[212:215], v[126:129]
	v_mfma_f32_16x16x32_bf16 v[122:125], v[180:183], v[212:215], v[122:125]
	v_mfma_f32_16x16x32_bf16 v[110:113], v[134:137], v[230:233], v[110:113]
	v_mfma_f32_16x16x32_bf16 v[106:109], v[180:183], v[230:233], v[106:109]
	v_mfma_f32_16x16x32_bf16 v[94:97], v[134:137], v[238:241], v[94:97]
	v_mfma_f32_16x16x32_bf16 v[90:93], v[180:183], v[238:241], v[90:93]
	v_mfma_f32_16x16x32_bf16 v[78:81], v[134:137], v[246:249], v[78:81]
	v_mfma_f32_16x16x32_bf16 v[74:77], v[180:183], v[246:249], v[74:77]
	s_setprio 0
	s_setprio 1
	v_mfma_f32_16x16x32_bf16 v[118:121], v[192:195], v[208:211], v[118:121]
	v_mfma_f32_16x16x32_bf16 v[114:117], v[200:203], v[208:211], v[114:117]
	v_mfma_f32_16x16x32_bf16 v[102:105], v[192:195], v[226:229], v[102:105]
	v_mfma_f32_16x16x32_bf16 v[98:101], v[200:203], v[226:229], v[98:101]
	v_mfma_f32_16x16x32_bf16 v[86:89], v[192:195], v[234:237], v[86:89]
	v_mfma_f32_16x16x32_bf16 v[82:85], v[200:203], v[234:237], v[82:85]
	v_mfma_f32_16x16x32_bf16 v[70:73], v[192:195], v[242:245], v[70:73]
	v_mfma_f32_16x16x32_bf16 v[66:69], v[200:203], v[242:245], v[66:69]
	v_mfma_f32_16x16x32_bf16 v[118:121], v[196:199], v[212:215], v[118:121]
	v_mfma_f32_16x16x32_bf16 v[114:117], v[204:207], v[212:215], v[114:117]
	v_mfma_f32_16x16x32_bf16 v[102:105], v[196:199], v[230:233], v[102:105]
	v_mfma_f32_16x16x32_bf16 v[98:101], v[204:207], v[230:233], v[98:101]
	v_mfma_f32_16x16x32_bf16 v[86:89], v[196:199], v[238:241], v[86:89]
	v_mfma_f32_16x16x32_bf16 v[82:85], v[204:207], v[238:241], v[82:85]
	v_mfma_f32_16x16x32_bf16 v[70:73], v[196:199], v[246:249], v[70:73]
	v_mfma_f32_16x16x32_bf16 v[66:69], v[204:207], v[246:249], v[66:69]
	s_setprio 0
	s_barrier
	s_mov_b64 s[54:55], 0x80
	s_add_i32 s14, s82, s65
	v_lshl_add_u64 v[184:185], v[184:185], 0, s[54:55]
	s_mov_b32 m0, s14
	ds_read_b128 v[208:211], v190 offset:49152
	ds_read_b128 v[212:215], v190 offset:50176
	ds_read_b128 v[226:229], v190 offset:51200
	ds_read_b128 v[230:233], v190 offset:52224
	ds_read_b128 v[234:237], v190 offset:53248
	ds_read_b128 v[238:241], v190 offset:54272
	ds_read_b128 v[242:245], v190 offset:55296
	ds_read_b128 v[246:249], v190 offset:56320
	global_load_lds_dwordx4 v[184:185], off
	s_add_i32 m0, s14, 0x2000
	s_add_u32 s14, s52, 0x40080
	v_lshl_add_u64 v[184:185], v[216:217], 0, s[54:55]
	s_addc_u32 s15, s53, 0
	s_add_i32 s52, s83, s65
	global_load_lds_dwordx4 v[184:185], off
	v_lshl_add_u64 v[184:185], s[14:15], 0, v[140:141]
	s_mov_b32 m0, s52
	s_mov_b64 s[82:83], 0x80
	global_load_lds_dwordx4 v[184:185], off
	v_lshl_add_u64 v[184:185], s[14:15], 0, v[144:145]
	s_add_i32 m0, s52, 0x2000
	s_nop 0
	global_load_lds_dwordx4 v[184:185], off
	v_lshl_add_u64 v[184:185], v[218:219], 0, s[82:83]
	s_mov_b32 m0, s71
	s_nop 0
	global_load_lds_dwordx4 v[184:185], off
	v_lshl_add_u64 v[184:185], v[220:221], 0, s[82:83]
	s_mov_b32 m0, s74
	s_nop 0
	global_load_lds_dwordx4 v[184:185], off
	s_waitcnt vmcnt(8)
	s_waitcnt lgkmcnt(0)
	s_barrier
	s_setprio 1
	v_mfma_f32_16x16x32_bf16 v[62:65], v[130:133], v[208:211], v[62:65]
	v_mfma_f32_16x16x32_bf16 v[58:61], v[176:179], v[208:211], v[58:61]
	v_mfma_f32_16x16x32_bf16 v[46:49], v[130:133], v[226:229], v[46:49]
	v_mfma_f32_16x16x32_bf16 v[42:45], v[176:179], v[226:229], v[42:45]
	v_mfma_f32_16x16x32_bf16 v[30:33], v[130:133], v[234:237], v[30:33]
	v_mfma_f32_16x16x32_bf16 v[26:29], v[176:179], v[234:237], v[26:29]
	v_mfma_f32_16x16x32_bf16 v[14:17], v[130:133], v[242:245], v[14:17]
	v_mfma_f32_16x16x32_bf16 v[10:13], v[176:179], v[242:245], v[10:13]
	v_mfma_f32_16x16x32_bf16 v[62:65], v[134:137], v[212:215], v[62:65]
	v_mfma_f32_16x16x32_bf16 v[58:61], v[180:183], v[212:215], v[58:61]
	v_mfma_f32_16x16x32_bf16 v[46:49], v[134:137], v[230:233], v[46:49]
	v_mfma_f32_16x16x32_bf16 v[42:45], v[180:183], v[230:233], v[42:45]
	v_mfma_f32_16x16x32_bf16 v[30:33], v[134:137], v[238:241], v[30:33]
	v_mfma_f32_16x16x32_bf16 v[26:29], v[180:183], v[238:241], v[26:29]
	v_mfma_f32_16x16x32_bf16 v[14:17], v[134:137], v[246:249], v[14:17]
	v_mfma_f32_16x16x32_bf16 v[10:13], v[180:183], v[246:249], v[10:13]
	s_setprio 0
	s_setprio 1
	v_mfma_f32_16x16x32_bf16 v[54:57], v[192:195], v[208:211], v[54:57]
	v_mfma_f32_16x16x32_bf16 v[50:53], v[200:203], v[208:211], v[50:53]
	v_mfma_f32_16x16x32_bf16 v[38:41], v[192:195], v[226:229], v[38:41]
	v_mfma_f32_16x16x32_bf16 v[34:37], v[200:203], v[226:229], v[34:37]
	v_mfma_f32_16x16x32_bf16 v[22:25], v[192:195], v[234:237], v[22:25]
	v_mfma_f32_16x16x32_bf16 v[18:21], v[200:203], v[234:237], v[18:21]
	v_mfma_f32_16x16x32_bf16 v[6:9], v[192:195], v[242:245], v[6:9]
	v_mfma_f32_16x16x32_bf16 v[2:5], v[200:203], v[242:245], v[2:5]
	v_mfma_f32_16x16x32_bf16 v[54:57], v[196:199], v[212:215], v[54:57]
	v_mfma_f32_16x16x32_bf16 v[50:53], v[204:207], v[212:215], v[50:53]
	v_mfma_f32_16x16x32_bf16 v[38:41], v[196:199], v[230:233], v[38:41]
	v_mfma_f32_16x16x32_bf16 v[34:37], v[204:207], v[230:233], v[34:37]
	v_mfma_f32_16x16x32_bf16 v[22:25], v[196:199], v[238:241], v[22:25]
	v_mfma_f32_16x16x32_bf16 v[18:21], v[204:207], v[238:241], v[18:21]
	v_mfma_f32_16x16x32_bf16 v[6:9], v[196:199], v[246:249], v[6:9]
	v_mfma_f32_16x16x32_bf16 v[2:5], v[204:207], v[246:249], v[2:5]
	s_setprio 0
	s_barrier
	s_add_i32 s81, s81, 2
	s_add_u32 s79, s79, 0x100
	s_addc_u32 s80, s80, 0
	s_cmp_gt_u32 s81, 13
	s_cbranch_scc1 .LBB0_222
	s_mov_b64 s[14:15], s[50:51]
	s_branch .LBB0_216

.LBB0_324:
	s_ashr_i32 s43, s42, 31
	s_lshl_b64 s[44:45], s[42:43], 19
	s_add_u32 s44, s60, s44
	s_addc_u32 s45, s61, s45
	s_and_b64 s[46:47], s[12:13], exec
	s_cselect_b32 s56, s45, s15
	s_cselect_b32 s57, s44, s14
	s_ashr_i32 s41, s40, 31
	s_lshl_b64 s[46:47], s[40:41], 19
	s_add_u32 s46, s16, s46
	s_addc_u32 s47, s17, s47
	s_and_b64 s[50:51], s[12:13], exec
	s_cselect_b32 s41, s47, s49
	s_cselect_b32 s71, s46, s48
	s_lshl_b64 s[50:51], s[42:43], 10
	s_add_u32 s43, s33, s50
	s_addc_u32 s74, s58, s51
	s_add_u32 s75, s48, 0x100
	s_addc_u32 s76, s49, 0
	s_mov_b32 s77, -2
	s_cmp_eq_u32 s77, 12
	s_cselect_b64 s[50:51], -1, 0
	s_and_b64 s[48:49], s[12:13], s[50:51]
	s_andn2_b64 vcc, exec, s[48:49]
	s_cbranch_vccnz .Lpeel325_329
	v_mov_b32_e32 v0, v165
	s_nop 0
	v_readfirstlane_b32 s48, v0
	s_ashr_i32 s49, s48, 6
	s_cmp_gt_i32 s49, 3
	s_cbranch_scc1 .Lpeel325_328
	s_and_b64 s[52:53], s[2:3], exec
	s_cselect_b32 s52, 0x1400, 0
	s_add_i32 s52, s52, 0
	s_lshl_b32 s49, s49, 8
	s_add_i32 s49, s52, s49
	s_andn2_b32 s48, s48, 63
	s_add_i32 m0, s49, 0x20400
	s_ashr_i32 s49, s48, 31
	s_lshl_b64 s[48:49], s[48:49], 2
	s_add_u32 s48, s43, s48
	v_and_b32_e32 v0, 63, v0
	s_addc_u32 s49, s74, s49
	v_lshlrev_b32_e32 v0, 2, v0
	global_load_lds_dword v0, s[48:49]

.Lpeel325_329:
	s_add_u32 s48, s14, 0x100
	s_addc_u32 s49, s15, 0
	s_and_b64 s[50:51], s[50:51], exec
	s_cselect_b32 s53, s56, s49
	s_cselect_b32 s52, s57, s48
	s_cselect_b32 s51, s41, s76
	s_cselect_b32 s50, s71, s75
	s_add_i32 s78, 0, 0x10000
	v_add_u32_e32 v0, s78, v187
	s_add_i32 s79, 0, 0x14000
	ds_read_b128 v[130:133], v0
	ds_read_b128 v[134:137], v0 offset:1024
	ds_read_b128 v[176:179], v0 offset:2048
	ds_read_b128 v[180:183], v0 offset:3072
	v_add_u32_e32 v0, s79, v187
	ds_read_b128 v[192:195], v0
	ds_read_b128 v[196:199], v0 offset:1024
	ds_read_b128 v[200:203], v0 offset:2048
	ds_read_b128 v[204:207], v0 offset:3072
	v_lshl_add_u64 v[184:185], s[14:15], 0, v[172:173]
	s_add_i32 m0, s62, 0xc000
	ds_read_b128 v[208:211], v190
	ds_read_b128 v[212:215], v190 offset:1024
	ds_read_b128 v[226:229], v190 offset:2048
	ds_read_b128 v[230:233], v190 offset:3072
	ds_read_b128 v[234:237], v190 offset:4096
	ds_read_b128 v[238:241], v190 offset:5120
	ds_read_b128 v[242:245], v190 offset:6144
	ds_read_b128 v[246:249], v190 offset:7168
	global_load_lds_dwordx4 v[184:185], off
	v_lshl_add_u64 v[184:185], s[14:15], 0, v[174:175]
	s_add_i32 m0, s62, 0xe000
	s_nop 0
	global_load_lds_dwordx4 v[184:185], off
	s_waitcnt vmcnt(8)
	s_waitcnt lgkmcnt(0)
	s_barrier
	s_setprio 1
	v_mfma_f32_16x16x32_bf16 v[126:129], v[130:133], v[208:211], 0
	v_mfma_f32_16x16x32_bf16 v[122:125], v[176:179], v[208:211], 0
	v_mfma_f32_16x16x32_bf16 v[110:113], v[130:133], v[226:229], 0
	v_mfma_f32_16x16x32_bf16 v[106:109], v[176:179], v[226:229], 0
	v_mfma_f32_16x16x32_bf16 v[94:97], v[130:133], v[234:237], 0
	v_mfma_f32_16x16x32_bf16 v[90:93], v[176:179], v[234:237], 0
	v_mfma_f32_16x16x32_bf16 v[78:81], v[130:133], v[242:245], 0
	v_mfma_f32_16x16x32_bf16 v[74:77], v[176:179], v[242:245], 0
	v_mfma_f32_16x16x32_bf16 v[126:129], v[134:137], v[212:215], v[126:129]
	v_mfma_f32_16x16x32_bf16 v[122:125], v[180:183], v[212:215], v[122:125]
	v_mfma_f32_16x16x32_bf16 v[110:113], v[134:137], v[230:233], v[110:113]
	v_mfma_f32_16x16x32_bf16 v[106:109], v[180:183], v[230:233], v[106:109]
	v_mfma_f32_16x16x32_bf16 v[94:97], v[134:137], v[238:241], v[94:97]
	v_mfma_f32_16x16x32_bf16 v[90:93], v[180:183], v[238:241], v[90:93]
	v_mfma_f32_16x16x32_bf16 v[78:81], v[134:137], v[246:249], v[78:81]
	v_mfma_f32_16x16x32_bf16 v[74:77], v[180:183], v[246:249], v[74:77]
	s_setprio 0
	s_setprio 1
	v_mfma_f32_16x16x32_bf16 v[118:121], v[192:195], v[208:211], 0
	v_mfma_f32_16x16x32_bf16 v[114:117], v[200:203], v[208:211], 0
	v_mfma_f32_16x16x32_bf16 v[102:105], v[192:195], v[226:229], 0
	v_mfma_f32_16x16x32_bf16 v[98:101], v[200:203], v[226:229], 0
	v_mfma_f32_16x16x32_bf16 v[86:89], v[192:195], v[234:237], 0
	v_mfma_f32_16x16x32_bf16 v[82:85], v[200:203], v[234:237], 0
	v_mfma_f32_16x16x32_bf16 v[70:73], v[192:195], v[242:245], 0
	v_mfma_f32_16x16x32_bf16 v[66:69], v[200:203], v[242:245], 0
	v_mfma_f32_16x16x32_bf16 v[118:121], v[196:199], v[212:215], v[118:121]
	v_mfma_f32_16x16x32_bf16 v[114:117], v[204:207], v[212:215], v[114:117]
	v_mfma_f32_16x16x32_bf16 v[102:105], v[196:199], v[230:233], v[102:105]
	v_mfma_f32_16x16x32_bf16 v[98:101], v[204:207], v[230:233], v[98:101]
	v_mfma_f32_16x16x32_bf16 v[86:89], v[196:199], v[238:241], v[86:89]
	v_mfma_f32_16x16x32_bf16 v[82:85], v[204:207], v[238:241], v[82:85]
	v_mfma_f32_16x16x32_bf16 v[70:73], v[196:199], v[246:249], v[70:73]
	v_mfma_f32_16x16x32_bf16 v[66:69], v[204:207], v[246:249], v[66:69]
	s_setprio 0
	s_barrier
	s_add_i32 s14, s78, s59
	v_lshl_add_u64 v[184:185], s[50:51], 0, v[140:141]
	s_mov_b32 m0, s14
	ds_read_b128 v[208:211], v190 offset:16384
	ds_read_b128 v[212:215], v190 offset:17408
	ds_read_b128 v[226:229], v190 offset:18432
	ds_read_b128 v[230:233], v190 offset:19456
	ds_read_b128 v[234:237], v190 offset:20480
	ds_read_b128 v[238:241], v190 offset:21504
	ds_read_b128 v[242:245], v190 offset:22528
	ds_read_b128 v[246:249], v190 offset:23552
	global_load_lds_dwordx4 v[184:185], off
	s_add_i32 m0, s14, 0x2000
	s_add_u32 s14, s50, 0x40000
	v_lshl_add_u64 v[216:217], s[50:51], 0, v[144:145]
	s_addc_u32 s15, s51, 0
	s_add_i32 s78, s79, s59
	global_load_lds_dwordx4 v[216:217], off
	v_lshl_add_u64 v[250:251], s[14:15], 0, v[140:141]
	s_mov_b32 m0, s78
	v_lshl_add_u64 v[218:219], s[52:53], 0, v[142:143]
	global_load_lds_dwordx4 v[250:251], off
	v_lshl_add_u64 v[250:251], s[14:15], 0, v[144:145]
	s_add_i32 m0, s78, 0x2000
	s_nop 0
	global_load_lds_dwordx4 v[250:251], off
	v_lshl_add_u64 v[250:251], s[52:53], 0, v[138:139]
	s_mov_b32 m0, s62
	s_nop 0
	global_load_lds_dwordx4 v[250:251], off
	s_mov_b32 m0, s63
	s_nop 0
	global_load_lds_dwordx4 v[218:219], off
	s_waitcnt vmcnt(8)
	s_waitcnt lgkmcnt(0)
	s_barrier
	s_setprio 1
	v_mfma_f32_16x16x32_bf16 v[62:65], v[130:133], v[208:211], 0
	v_mfma_f32_16x16x32_bf16 v[58:61], v[176:179], v[208:211], 0
	v_mfma_f32_16x16x32_bf16 v[46:49], v[130:133], v[226:229], 0
	v_mfma_f32_16x16x32_bf16 v[42:45], v[176:179], v[226:229], 0
	v_mfma_f32_16x16x32_bf16 v[30:33], v[130:133], v[234:237], 0
	v_mfma_f32_16x16x32_bf16 v[26:29], v[176:179], v[234:237], 0
	v_mfma_f32_16x16x32_bf16 v[14:17], v[130:133], v[242:245], 0
	v_mfma_f32_16x16x32_bf16 v[10:13], v[176:179], v[242:245], 0
	v_mfma_f32_16x16x32_bf16 v[62:65], v[134:137], v[212:215], v[62:65]
	v_mfma_f32_16x16x32_bf16 v[58:61], v[180:183], v[212:215], v[58:61]
	v_mfma_f32_16x16x32_bf16 v[46:49], v[134:137], v[230:233], v[46:49]
	v_mfma_f32_16x16x32_bf16 v[42:45], v[180:183], v[230:233], v[42:45]
	v_mfma_f32_16x16x32_bf16 v[30:33], v[134:137], v[238:241], v[30:33]
	v_mfma_f32_16x16x32_bf16 v[26:29], v[180:183], v[238:241], v[26:29]
	v_mfma_f32_16x16x32_bf16 v[14:17], v[134:137], v[246:249], v[14:17]
	v_mfma_f32_16x16x32_bf16 v[10:13], v[180:183], v[246:249], v[10:13]
	s_setprio 0
	s_setprio 1
	v_mfma_f32_16x16x32_bf16 v[54:57], v[192:195], v[208:211], 0
	v_mfma_f32_16x16x32_bf16 v[50:53], v[200:203], v[208:211], 0
	v_mfma_f32_16x16x32_bf16 v[38:41], v[192:195], v[226:229], 0
	v_mfma_f32_16x16x32_bf16 v[34:37], v[200:203], v[226:229], 0
	v_mfma_f32_16x16x32_bf16 v[22:25], v[192:195], v[234:237], 0
	v_mfma_f32_16x16x32_bf16 v[18:21], v[200:203], v[234:237], 0
	v_mfma_f32_16x16x32_bf16 v[6:9], v[192:195], v[242:245], 0
	v_mfma_f32_16x16x32_bf16 v[2:5], v[200:203], v[242:245], 0
	v_mfma_f32_16x16x32_bf16 v[54:57], v[196:199], v[212:215], v[54:57]
	v_mfma_f32_16x16x32_bf16 v[50:53], v[204:207], v[212:215], v[50:53]
	v_mfma_f32_16x16x32_bf16 v[38:41], v[196:199], v[230:233], v[38:41]
	v_mfma_f32_16x16x32_bf16 v[34:37], v[204:207], v[230:233], v[34:37]
	v_mfma_f32_16x16x32_bf16 v[22:25], v[196:199], v[238:241], v[22:25]
	v_mfma_f32_16x16x32_bf16 v[18:21], v[204:207], v[238:241], v[18:21]
	v_mfma_f32_16x16x32_bf16 v[6:9], v[196:199], v[246:249], v[6:9]
	v_mfma_f32_16x16x32_bf16 v[2:5], v[204:207], v[246:249], v[2:5]
	s_setprio 0
	s_barrier
	s_add_i32 s78, 0, 0x18000
	v_add_u32_e32 v0, s78, v187
	s_add_i32 s79, 0, 0x1c000
	ds_read_b128 v[130:133], v0
	ds_read_b128 v[134:137], v0 offset:1024
	ds_read_b128 v[176:179], v0 offset:2048
	ds_read_b128 v[180:183], v0 offset:3072
	v_add_u32_e32 v0, s79, v187
	ds_read_b128 v[192:195], v0
	ds_read_b128 v[196:199], v0 offset:1024
	ds_read_b128 v[200:203], v0 offset:2048
	ds_read_b128 v[204:207], v0 offset:3072
	s_add_u32 s14, s52, 0x40000
	s_addc_u32 s15, s53, 0
	s_mov_b32 m0, s64
	v_lshl_add_u64 v[220:221], s[14:15], 0, v[138:139]
	ds_read_b128 v[208:211], v190 offset:32768
	ds_read_b128 v[212:215], v190 offset:33792
	ds_read_b128 v[226:229], v190 offset:34816
	ds_read_b128 v[230:233], v190 offset:35840
	ds_read_b128 v[234:237], v190 offset:36864
	ds_read_b128 v[238:241], v190 offset:37888
	ds_read_b128 v[242:245], v190 offset:38912
	ds_read_b128 v[246:249], v190 offset:39936
	global_load_lds_dwordx4 v[220:221], off
	v_lshl_add_u64 v[220:221], s[14:15], 0, v[142:143]
	s_mov_b32 m0, s65
	s_nop 0
	global_load_lds_dwordx4 v[220:221], off
	s_waitcnt vmcnt(8)
	s_waitcnt lgkmcnt(0)
	s_barrier
	s_setprio 1
	v_mfma_f32_16x16x32_bf16 v[126:129], v[130:133], v[208:211], v[126:129]
	v_mfma_f32_16x16x32_bf16 v[122:125], v[176:179], v[208:211], v[122:125]
	v_mfma_f32_16x16x32_bf16 v[110:113], v[130:133], v[226:229], v[110:113]
	v_mfma_f32_16x16x32_bf16 v[106:109], v[176:179], v[226:229], v[106:109]
	v_mfma_f32_16x16x32_bf16 v[94:97], v[130:133], v[234:237], v[94:97]
	v_mfma_f32_16x16x32_bf16 v[90:93], v[176:179], v[234:237], v[90:93]
	v_mfma_f32_16x16x32_bf16 v[78:81], v[130:133], v[242:245], v[78:81]
	v_mfma_f32_16x16x32_bf16 v[74:77], v[176:179], v[242:245], v[74:77]
	v_mfma_f32_16x16x32_bf16 v[126:129], v[134:137], v[212:215], v[126:129]
	v_mfma_f32_16x16x32_bf16 v[122:125], v[180:183], v[212:215], v[122:125]
	v_mfma_f32_16x16x32_bf16 v[110:113], v[134:137], v[230:233], v[110:113]
	v_mfma_f32_16x16x32_bf16 v[106:109], v[180:183], v[230:233], v[106:109]
	v_mfma_f32_16x16x32_bf16 v[94:97], v[134:137], v[238:241], v[94:97]
	v_mfma_f32_16x16x32_bf16 v[90:93], v[180:183], v[238:241], v[90:93]
	v_mfma_f32_16x16x32_bf16 v[78:81], v[134:137], v[246:249], v[78:81]
	v_mfma_f32_16x16x32_bf16 v[74:77], v[180:183], v[246:249], v[74:77]
	s_setprio 0
	s_setprio 1
	v_mfma_f32_16x16x32_bf16 v[118:121], v[192:195], v[208:211], v[118:121]
	v_mfma_f32_16x16x32_bf16 v[114:117], v[200:203], v[208:211], v[114:117]
	v_mfma_f32_16x16x32_bf16 v[102:105], v[192:195], v[226:229], v[102:105]
	v_mfma_f32_16x16x32_bf16 v[98:101], v[200:203], v[226:229], v[98:101]
	v_mfma_f32_16x16x32_bf16 v[86:89], v[192:195], v[234:237], v[86:89]
	v_mfma_f32_16x16x32_bf16 v[82:85], v[200:203], v[234:237], v[82:85]
	v_mfma_f32_16x16x32_bf16 v[70:73], v[192:195], v[242:245], v[70:73]
	v_mfma_f32_16x16x32_bf16 v[66:69], v[200:203], v[242:245], v[66:69]
	v_mfma_f32_16x16x32_bf16 v[118:121], v[196:199], v[212:215], v[118:121]
	v_mfma_f32_16x16x32_bf16 v[114:117], v[204:207], v[212:215], v[114:117]
	v_mfma_f32_16x16x32_bf16 v[102:105], v[196:199], v[230:233], v[102:105]
	v_mfma_f32_16x16x32_bf16 v[98:101], v[204:207], v[230:233], v[98:101]
	v_mfma_f32_16x16x32_bf16 v[86:89], v[196:199], v[238:241], v[86:89]
	v_mfma_f32_16x16x32_bf16 v[82:85], v[204:207], v[238:241], v[82:85]
	v_mfma_f32_16x16x32_bf16 v[70:73], v[196:199], v[246:249], v[70:73]
	v_mfma_f32_16x16x32_bf16 v[66:69], v[204:207], v[246:249], v[66:69]
	s_setprio 0
	s_barrier
	s_add_i32 s14, s78, s59
	v_lshl_add_u64 v[184:185], v[184:185], 0, s[82:83]
	s_mov_b32 m0, s14
	ds_read_b128 v[208:211], v190 offset:49152
	ds_read_b128 v[212:215], v190 offset:50176
	ds_read_b128 v[226:229], v190 offset:51200
	ds_read_b128 v[230:233], v190 offset:52224
	ds_read_b128 v[234:237], v190 offset:53248
	ds_read_b128 v[238:241], v190 offset:54272
	ds_read_b128 v[242:245], v190 offset:55296
	ds_read_b128 v[246:249], v190 offset:56320
	global_load_lds_dwordx4 v[184:185], off
	s_add_i32 m0, s14, 0x2000
	s_add_u32 s14, s50, 0x40080
	v_lshl_add_u64 v[184:185], v[216:217], 0, s[82:83]
	s_addc_u32 s15, s51, 0
	s_add_i32 s50, s79, s59
	global_load_lds_dwordx4 v[184:185], off
	v_lshl_add_u64 v[184:185], s[14:15], 0, v[140:141]
	s_mov_b32 m0, s50
	s_nop 0
	global_load_lds_dwordx4 v[184:185], off
	v_lshl_add_u64 v[184:185], s[14:15], 0, v[144:145]
	s_add_i32 m0, s50, 0x2000
	s_nop 0
	global_load_lds_dwordx4 v[184:185], off
	v_lshl_add_u64 v[184:185], v[250:251], 0, s[82:83]
	s_mov_b32 m0, s67
	s_nop 0
	global_load_lds_dwordx4 v[184:185], off
	v_lshl_add_u64 v[184:185], v[218:219], 0, s[82:83]
	s_mov_b32 m0, s68
	s_nop 0
	global_load_lds_dwordx4 v[184:185], off
	s_waitcnt vmcnt(8)
	s_waitcnt lgkmcnt(0)
	s_barrier
	s_setprio 1
	v_mfma_f32_16x16x32_bf16 v[62:65], v[130:133], v[208:211], v[62:65]
	v_mfma_f32_16x16x32_bf16 v[58:61], v[176:179], v[208:211], v[58:61]
	v_mfma_f32_16x16x32_bf16 v[46:49], v[130:133], v[226:229], v[46:49]
	v_mfma_f32_16x16x32_bf16 v[42:45], v[176:179], v[226:229], v[42:45]
	v_mfma_f32_16x16x32_bf16 v[30:33], v[130:133], v[234:237], v[30:33]
	v_mfma_f32_16x16x32_bf16 v[26:29], v[176:179], v[234:237], v[26:29]
	v_mfma_f32_16x16x32_bf16 v[14:17], v[130:133], v[242:245], v[14:17]
	v_mfma_f32_16x16x32_bf16 v[10:13], v[176:179], v[242:245], v[10:13]
	v_mfma_f32_16x16x32_bf16 v[62:65], v[134:137], v[212:215], v[62:65]
	v_mfma_f32_16x16x32_bf16 v[58:61], v[180:183], v[212:215], v[58:61]
	v_mfma_f32_16x16x32_bf16 v[46:49], v[134:137], v[230:233], v[46:49]
	v_mfma_f32_16x16x32_bf16 v[42:45], v[180:183], v[230:233], v[42:45]
	v_mfma_f32_16x16x32_bf16 v[30:33], v[134:137], v[238:241], v[30:33]
	v_mfma_f32_16x16x32_bf16 v[26:29], v[180:183], v[238:241], v[26:29]
	v_mfma_f32_16x16x32_bf16 v[14:17], v[134:137], v[246:249], v[14:17]
	v_mfma_f32_16x16x32_bf16 v[10:13], v[180:183], v[246:249], v[10:13]
	s_setprio 0
	s_setprio 1
	v_mfma_f32_16x16x32_bf16 v[54:57], v[192:195], v[208:211], v[54:57]
	v_mfma_f32_16x16x32_bf16 v[50:53], v[200:203], v[208:211], v[50:53]
	v_mfma_f32_16x16x32_bf16 v[38:41], v[192:195], v[226:229], v[38:41]
	v_mfma_f32_16x16x32_bf16 v[34:37], v[200:203], v[226:229], v[34:37]
	v_mfma_f32_16x16x32_bf16 v[22:25], v[192:195], v[234:237], v[22:25]
	v_mfma_f32_16x16x32_bf16 v[18:21], v[200:203], v[234:237], v[18:21]
	v_mfma_f32_16x16x32_bf16 v[6:9], v[192:195], v[242:245], v[6:9]
	v_mfma_f32_16x16x32_bf16 v[2:5], v[200:203], v[242:245], v[2:5]
	v_mfma_f32_16x16x32_bf16 v[54:57], v[196:199], v[212:215], v[54:57]
	v_mfma_f32_16x16x32_bf16 v[50:53], v[204:207], v[212:215], v[50:53]
	v_mfma_f32_16x16x32_bf16 v[38:41], v[196:199], v[230:233], v[38:41]
	v_mfma_f32_16x16x32_bf16 v[34:37], v[204:207], v[230:233], v[34:37]
	v_mfma_f32_16x16x32_bf16 v[22:25], v[196:199], v[238:241], v[22:25]
	v_mfma_f32_16x16x32_bf16 v[18:21], v[204:207], v[238:241], v[18:21]
	v_mfma_f32_16x16x32_bf16 v[6:9], v[196:199], v[246:249], v[6:9]
	v_mfma_f32_16x16x32_bf16 v[2:5], v[204:207], v[246:249], v[2:5]
	s_setprio 0
	s_barrier
	s_add_i32 s77, s77, 2
	s_add_u32 s75, s75, 0x100
	s_addc_u32 s76, s76, 0
	s_cmp_gt_u32 s77, 13
	s_cbranch_scc1 .LBB0_331
	s_mov_b64 s[14:15], s[48:49]
	s_branch .LBB0_325

.LBB0_438:
	s_ashr_i32 s17, s16, 31
	s_lshl_b64 s[18:19], s[16:17], 19
	s_add_u32 s18, s30, s18
	s_addc_u32 s19, s31, s19
	s_and_b64 s[20:21], s[12:13], exec
	s_cselect_b32 s49, s19, s5
	s_cselect_b32 s50, s18, s4
	s_ashr_i32 s15, s14, 31
	s_lshl_b64 s[20:21], s[14:15], 19
	s_add_u32 s20, s33, s20
	s_addc_u32 s21, s34, s21
	s_and_b64 s[24:25], s[12:13], exec
	s_cselect_b32 s15, s21, s23
	s_cselect_b32 s51, s20, s22
	s_lshl_b64 s[24:25], s[16:17], 10
	s_add_u32 s17, s28, s24
	s_addc_u32 s52, s29, s25
	s_add_u32 s53, s22, 0x100
	s_addc_u32 s54, s23, 0
	s_mov_b32 s55, -2
	s_cmp_eq_u32 s55, 12
	s_cselect_b64 s[24:25], -1, 0
	s_and_b64 s[22:23], s[12:13], s[24:25]
	s_andn2_b64 vcc, exec, s[22:23]
	s_cbranch_vccnz .Lpeel439_443
	v_mov_b32_e32 v0, v165
	s_nop 0
	v_readfirstlane_b32 s22, v0
	s_ashr_i32 s23, s22, 6
	s_cmp_gt_i32 s23, 3
	s_cbranch_scc1 .Lpeel439_442
	s_and_b64 s[26:27], s[8:9], exec
	s_cselect_b32 s26, 0x1400, 0
	s_add_i32 s26, s26, 0
	s_lshl_b32 s23, s23, 8
	s_add_i32 s23, s26, s23
	s_andn2_b32 s22, s22, 63
	s_add_i32 m0, s23, 0x20400
	s_ashr_i32 s23, s22, 31
	s_lshl_b64 s[22:23], s[22:23], 2
	s_add_u32 s22, s17, s22
	v_and_b32_e32 v0, 63, v0
	s_addc_u32 s23, s52, s23
	v_lshlrev_b32_e32 v0, 2, v0
	global_load_lds_dword v0, s[22:23]

.Lpeel439_443:
	s_add_u32 s22, s4, 0x100
	s_addc_u32 s23, s5, 0
	s_and_b64 s[24:25], s[24:25], exec
	s_cselect_b32 s27, s49, s23
	s_cselect_b32 s26, s50, s22
	s_cselect_b32 s25, s15, s54
	s_cselect_b32 s24, s51, s53
	s_add_i32 s56, 0, 0x10000
	v_add_u32_e32 v0, s56, v173
	s_add_i32 s57, 0, 0x14000
	ds_read_b128 v[178:181], v0
	ds_read_b128 v[182:185], v0 offset:1024
	ds_read_b128 v[186:189], v0 offset:2048
	ds_read_b128 v[190:193], v0 offset:3072
	v_add_u32_e32 v0, s57, v173
	ds_read_b128 v[194:197], v0
	ds_read_b128 v[198:201], v0 offset:1024
	ds_read_b128 v[202:205], v0 offset:2048
	ds_read_b128 v[206:209], v0 offset:3072
	v_lshl_add_u64 v[218:219], s[4:5], 0, v[138:139]
	s_add_i32 m0, s36, 0xc000
	ds_read_b128 v[210:213], v177
	ds_read_b128 v[214:217], v177 offset:1024
	ds_read_b128 v[226:229], v177 offset:2048
	ds_read_b128 v[230:233], v177 offset:3072
	ds_read_b128 v[234:237], v177 offset:4096
	ds_read_b128 v[238:241], v177 offset:5120
	ds_read_b128 v[242:245], v177 offset:6144
	ds_read_b128 v[246:249], v177 offset:7168
	global_load_lds_dwordx4 v[218:219], off
	v_lshl_add_u64 v[218:219], s[4:5], 0, v[140:141]
	s_add_i32 m0, s36, 0xe000
	s_nop 0
	global_load_lds_dwordx4 v[218:219], off
	s_waitcnt vmcnt(8)
	s_waitcnt lgkmcnt(0)
	s_barrier
	s_setprio 1
	v_mfma_f32_16x16x32_bf16 v[126:129], v[178:181], v[210:213], 0
	v_mfma_f32_16x16x32_bf16 v[122:125], v[186:189], v[210:213], 0
	v_mfma_f32_16x16x32_bf16 v[110:113], v[178:181], v[226:229], 0
	v_mfma_f32_16x16x32_bf16 v[106:109], v[186:189], v[226:229], 0
	v_mfma_f32_16x16x32_bf16 v[94:97], v[178:181], v[234:237], 0
	v_mfma_f32_16x16x32_bf16 v[90:93], v[186:189], v[234:237], 0
	v_mfma_f32_16x16x32_bf16 v[78:81], v[178:181], v[242:245], 0
	v_mfma_f32_16x16x32_bf16 v[74:77], v[186:189], v[242:245], 0
	v_mfma_f32_16x16x32_bf16 v[126:129], v[182:185], v[214:217], v[126:129]
	v_mfma_f32_16x16x32_bf16 v[122:125], v[190:193], v[214:217], v[122:125]
	v_mfma_f32_16x16x32_bf16 v[110:113], v[182:185], v[230:233], v[110:113]
	v_mfma_f32_16x16x32_bf16 v[106:109], v[190:193], v[230:233], v[106:109]
	v_mfma_f32_16x16x32_bf16 v[94:97], v[182:185], v[238:241], v[94:97]
	v_mfma_f32_16x16x32_bf16 v[90:93], v[190:193], v[238:241], v[90:93]
	v_mfma_f32_16x16x32_bf16 v[78:81], v[182:185], v[246:249], v[78:81]
	v_mfma_f32_16x16x32_bf16 v[74:77], v[190:193], v[246:249], v[74:77]
	s_setprio 0
	s_setprio 1
	v_mfma_f32_16x16x32_bf16 v[118:121], v[194:197], v[210:213], 0
	v_mfma_f32_16x16x32_bf16 v[114:117], v[202:205], v[210:213], 0
	v_mfma_f32_16x16x32_bf16 v[102:105], v[194:197], v[226:229], 0
	v_mfma_f32_16x16x32_bf16 v[98:101], v[202:205], v[226:229], 0
	v_mfma_f32_16x16x32_bf16 v[86:89], v[194:197], v[234:237], 0
	v_mfma_f32_16x16x32_bf16 v[82:85], v[202:205], v[234:237], 0
	v_mfma_f32_16x16x32_bf16 v[70:73], v[194:197], v[242:245], 0
	v_mfma_f32_16x16x32_bf16 v[66:69], v[202:205], v[242:245], 0
	v_mfma_f32_16x16x32_bf16 v[118:121], v[198:201], v[214:217], v[118:121]
	v_mfma_f32_16x16x32_bf16 v[114:117], v[206:209], v[214:217], v[114:117]
	v_mfma_f32_16x16x32_bf16 v[102:105], v[198:201], v[230:233], v[102:105]
	v_mfma_f32_16x16x32_bf16 v[98:101], v[206:209], v[230:233], v[98:101]
	v_mfma_f32_16x16x32_bf16 v[86:89], v[198:201], v[238:241], v[86:89]
	v_mfma_f32_16x16x32_bf16 v[82:85], v[206:209], v[238:241], v[82:85]
	v_mfma_f32_16x16x32_bf16 v[70:73], v[198:201], v[246:249], v[70:73]
	v_mfma_f32_16x16x32_bf16 v[66:69], v[206:209], v[246:249], v[66:69]
	s_setprio 0
	s_barrier
	s_add_i32 s4, s56, s35
	v_lshl_add_u64 v[218:219], s[24:25], 0, v[132:133]
	s_mov_b32 m0, s4
	ds_read_b128 v[210:213], v177 offset:16384
	ds_read_b128 v[214:217], v177 offset:17408
	ds_read_b128 v[226:229], v177 offset:18432
	ds_read_b128 v[230:233], v177 offset:19456
	ds_read_b128 v[234:237], v177 offset:20480
	ds_read_b128 v[238:241], v177 offset:21504
	ds_read_b128 v[242:245], v177 offset:22528
	ds_read_b128 v[246:249], v177 offset:23552
	global_load_lds_dwordx4 v[218:219], off
	s_add_i32 m0, s4, 0x2000
	s_add_u32 s4, s24, 0x40000
	v_lshl_add_u64 v[220:221], s[24:25], 0, v[136:137]
	s_addc_u32 s5, s25, 0
	s_add_i32 s56, s57, s35
	global_load_lds_dwordx4 v[220:221], off
	v_lshl_add_u64 v[250:251], s[4:5], 0, v[132:133]
	s_mov_b32 m0, s56
	v_lshl_add_u64 v[162:163], s[26:27], 0, v[134:135]
	global_load_lds_dwordx4 v[250:251], off
	v_lshl_add_u64 v[250:251], s[4:5], 0, v[136:137]
	s_add_i32 m0, s56, 0x2000
	s_nop 0
	global_load_lds_dwordx4 v[250:251], off
	v_lshl_add_u64 v[250:251], s[26:27], 0, v[130:131]
	s_mov_b32 m0, s36
	s_nop 0
	global_load_lds_dwordx4 v[250:251], off
	s_mov_b32 m0, s37
	s_nop 0
	global_load_lds_dwordx4 v[162:163], off
	s_waitcnt vmcnt(8)
	s_waitcnt lgkmcnt(0)
	s_barrier
	s_setprio 1
	v_mfma_f32_16x16x32_bf16 v[62:65], v[178:181], v[210:213], 0
	v_mfma_f32_16x16x32_bf16 v[58:61], v[186:189], v[210:213], 0
	v_mfma_f32_16x16x32_bf16 v[50:53], v[178:181], v[226:229], 0
	v_mfma_f32_16x16x32_bf16 v[42:45], v[186:189], v[226:229], 0
	v_mfma_f32_16x16x32_bf16 v[34:37], v[178:181], v[234:237], 0
	v_mfma_f32_16x16x32_bf16 v[26:29], v[186:189], v[234:237], 0
	v_mfma_f32_16x16x32_bf16 v[18:21], v[178:181], v[242:245], 0
	v_mfma_f32_16x16x32_bf16 v[10:13], v[186:189], v[242:245], 0
	v_mfma_f32_16x16x32_bf16 v[62:65], v[182:185], v[214:217], v[62:65]
	v_mfma_f32_16x16x32_bf16 v[58:61], v[190:193], v[214:217], v[58:61]
	v_mfma_f32_16x16x32_bf16 v[50:53], v[182:185], v[230:233], v[50:53]
	v_mfma_f32_16x16x32_bf16 v[42:45], v[190:193], v[230:233], v[42:45]
	v_mfma_f32_16x16x32_bf16 v[34:37], v[182:185], v[238:241], v[34:37]
	v_mfma_f32_16x16x32_bf16 v[26:29], v[190:193], v[238:241], v[26:29]
	v_mfma_f32_16x16x32_bf16 v[18:21], v[182:185], v[246:249], v[18:21]
	v_mfma_f32_16x16x32_bf16 v[10:13], v[190:193], v[246:249], v[10:13]
	s_setprio 0
	s_setprio 1
	v_mfma_f32_16x16x32_bf16 v[54:57], v[194:197], v[210:213], 0
	v_mfma_f32_16x16x32_bf16 v[46:49], v[202:205], v[210:213], 0
	v_mfma_f32_16x16x32_bf16 v[38:41], v[194:197], v[226:229], 0
	v_mfma_f32_16x16x32_bf16 v[30:33], v[202:205], v[226:229], 0
	v_mfma_f32_16x16x32_bf16 v[22:25], v[194:197], v[234:237], 0
	v_mfma_f32_16x16x32_bf16 v[14:17], v[202:205], v[234:237], 0
	v_mfma_f32_16x16x32_bf16 v[6:9], v[194:197], v[242:245], 0
	v_mfma_f32_16x16x32_bf16 v[2:5], v[202:205], v[242:245], 0
	v_mfma_f32_16x16x32_bf16 v[54:57], v[198:201], v[214:217], v[54:57]
	v_mfma_f32_16x16x32_bf16 v[46:49], v[206:209], v[214:217], v[46:49]
	v_mfma_f32_16x16x32_bf16 v[38:41], v[198:201], v[230:233], v[38:41]
	v_mfma_f32_16x16x32_bf16 v[30:33], v[206:209], v[230:233], v[30:33]
	v_mfma_f32_16x16x32_bf16 v[22:25], v[198:201], v[238:241], v[22:25]
	v_mfma_f32_16x16x32_bf16 v[14:17], v[206:209], v[238:241], v[14:17]
	v_mfma_f32_16x16x32_bf16 v[6:9], v[198:201], v[246:249], v[6:9]
	v_mfma_f32_16x16x32_bf16 v[2:5], v[206:209], v[246:249], v[2:5]
	s_setprio 0
	s_barrier
	s_add_i32 s56, 0, 0x18000
	v_add_u32_e32 v0, s56, v173
	s_add_i32 s57, 0, 0x1c000
	ds_read_b128 v[178:181], v0
	ds_read_b128 v[182:185], v0 offset:1024
	ds_read_b128 v[186:189], v0 offset:2048
	ds_read_b128 v[190:193], v0 offset:3072
	v_add_u32_e32 v0, s57, v173
	ds_read_b128 v[194:197], v0
	ds_read_b128 v[198:201], v0 offset:1024
	ds_read_b128 v[202:205], v0 offset:2048
	ds_read_b128 v[206:209], v0 offset:3072
	s_add_u32 s4, s26, 0x40000
	s_addc_u32 s5, s27, 0
	s_mov_b32 m0, s38
	v_lshl_add_u64 v[158:159], s[4:5], 0, v[130:131]
	ds_read_b128 v[210:213], v177 offset:32768
	ds_read_b128 v[214:217], v177 offset:33792
	ds_read_b128 v[226:229], v177 offset:34816
	ds_read_b128 v[230:233], v177 offset:35840
	ds_read_b128 v[234:237], v177 offset:36864
	ds_read_b128 v[238:241], v177 offset:37888
	ds_read_b128 v[242:245], v177 offset:38912
	ds_read_b128 v[246:249], v177 offset:39936
	global_load_lds_dwordx4 v[158:159], off
	v_lshl_add_u64 v[158:159], s[4:5], 0, v[134:135]
	s_mov_b32 m0, s39
	s_nop 0
	global_load_lds_dwordx4 v[158:159], off
	s_waitcnt vmcnt(8)
	s_waitcnt lgkmcnt(0)
	s_barrier
	s_setprio 1
	v_mfma_f32_16x16x32_bf16 v[126:129], v[178:181], v[210:213], v[126:129]
	v_mfma_f32_16x16x32_bf16 v[122:125], v[186:189], v[210:213], v[122:125]
	v_mfma_f32_16x16x32_bf16 v[110:113], v[178:181], v[226:229], v[110:113]
	v_mfma_f32_16x16x32_bf16 v[106:109], v[186:189], v[226:229], v[106:109]
	v_mfma_f32_16x16x32_bf16 v[94:97], v[178:181], v[234:237], v[94:97]
	v_mfma_f32_16x16x32_bf16 v[90:93], v[186:189], v[234:237], v[90:93]
	v_mfma_f32_16x16x32_bf16 v[78:81], v[178:181], v[242:245], v[78:81]
	v_mfma_f32_16x16x32_bf16 v[74:77], v[186:189], v[242:245], v[74:77]
	v_mfma_f32_16x16x32_bf16 v[126:129], v[182:185], v[214:217], v[126:129]
	v_mfma_f32_16x16x32_bf16 v[122:125], v[190:193], v[214:217], v[122:125]
	v_mfma_f32_16x16x32_bf16 v[110:113], v[182:185], v[230:233], v[110:113]
	v_mfma_f32_16x16x32_bf16 v[106:109], v[190:193], v[230:233], v[106:109]
	v_mfma_f32_16x16x32_bf16 v[94:97], v[182:185], v[238:241], v[94:97]
	v_mfma_f32_16x16x32_bf16 v[90:93], v[190:193], v[238:241], v[90:93]
	v_mfma_f32_16x16x32_bf16 v[78:81], v[182:185], v[246:249], v[78:81]
	v_mfma_f32_16x16x32_bf16 v[74:77], v[190:193], v[246:249], v[74:77]
	s_setprio 0
	s_setprio 1
	v_mfma_f32_16x16x32_bf16 v[118:121], v[194:197], v[210:213], v[118:121]
	v_mfma_f32_16x16x32_bf16 v[114:117], v[202:205], v[210:213], v[114:117]
	v_mfma_f32_16x16x32_bf16 v[102:105], v[194:197], v[226:229], v[102:105]
	v_mfma_f32_16x16x32_bf16 v[98:101], v[202:205], v[226:229], v[98:101]
	v_mfma_f32_16x16x32_bf16 v[86:89], v[194:197], v[234:237], v[86:89]
	v_mfma_f32_16x16x32_bf16 v[82:85], v[202:205], v[234:237], v[82:85]
	v_mfma_f32_16x16x32_bf16 v[70:73], v[194:197], v[242:245], v[70:73]
	v_mfma_f32_16x16x32_bf16 v[66:69], v[202:205], v[242:245], v[66:69]
	v_mfma_f32_16x16x32_bf16 v[118:121], v[198:201], v[214:217], v[118:121]
	v_mfma_f32_16x16x32_bf16 v[114:117], v[206:209], v[214:217], v[114:117]
	v_mfma_f32_16x16x32_bf16 v[102:105], v[198:201], v[230:233], v[102:105]
	v_mfma_f32_16x16x32_bf16 v[98:101], v[206:209], v[230:233], v[98:101]
	v_mfma_f32_16x16x32_bf16 v[86:89], v[198:201], v[238:241], v[86:89]
	v_mfma_f32_16x16x32_bf16 v[82:85], v[206:209], v[238:241], v[82:85]
	v_mfma_f32_16x16x32_bf16 v[70:73], v[198:201], v[246:249], v[70:73]
	v_mfma_f32_16x16x32_bf16 v[66:69], v[206:209], v[246:249], v[66:69]
	s_setprio 0
	s_barrier
	s_add_i32 s4, s56, s35
	v_lshl_add_u64 v[158:159], v[218:219], 0, s[82:83]
	s_mov_b32 m0, s4
	ds_read_b128 v[210:213], v177 offset:49152
	ds_read_b128 v[214:217], v177 offset:50176
	ds_read_b128 v[226:229], v177 offset:51200
	ds_read_b128 v[230:233], v177 offset:52224
	ds_read_b128 v[234:237], v177 offset:53248
	ds_read_b128 v[238:241], v177 offset:54272
	ds_read_b128 v[242:245], v177 offset:55296
	ds_read_b128 v[246:249], v177 offset:56320
	global_load_lds_dwordx4 v[158:159], off
	s_add_i32 m0, s4, 0x2000
	s_add_u32 s4, s24, 0x40080
	v_lshl_add_u64 v[158:159], v[220:221], 0, s[82:83]
	s_addc_u32 s5, s25, 0
	s_add_i32 s24, s57, s35
	global_load_lds_dwordx4 v[158:159], off
	v_lshl_add_u64 v[158:159], s[4:5], 0, v[132:133]
	s_mov_b32 m0, s24
	s_nop 0
	global_load_lds_dwordx4 v[158:159], off
	v_lshl_add_u64 v[158:159], s[4:5], 0, v[136:137]
	s_add_i32 m0, s24, 0x2000
	s_nop 0
	global_load_lds_dwordx4 v[158:159], off
	v_lshl_add_u64 v[158:159], v[250:251], 0, s[82:83]
	s_mov_b32 m0, s41
	s_nop 0
	global_load_lds_dwordx4 v[158:159], off
	v_lshl_add_u64 v[158:159], v[162:163], 0, s[82:83]
	s_mov_b32 m0, s42
	s_nop 0
	global_load_lds_dwordx4 v[158:159], off
	s_waitcnt vmcnt(8)
	s_waitcnt lgkmcnt(0)
	s_barrier
	s_setprio 1
	v_mfma_f32_16x16x32_bf16 v[62:65], v[178:181], v[210:213], v[62:65]
	v_mfma_f32_16x16x32_bf16 v[58:61], v[186:189], v[210:213], v[58:61]
	v_mfma_f32_16x16x32_bf16 v[50:53], v[178:181], v[226:229], v[50:53]
	v_mfma_f32_16x16x32_bf16 v[42:45], v[186:189], v[226:229], v[42:45]
	v_mfma_f32_16x16x32_bf16 v[34:37], v[178:181], v[234:237], v[34:37]
	v_mfma_f32_16x16x32_bf16 v[26:29], v[186:189], v[234:237], v[26:29]
	v_mfma_f32_16x16x32_bf16 v[18:21], v[178:181], v[242:245], v[18:21]
	v_mfma_f32_16x16x32_bf16 v[10:13], v[186:189], v[242:245], v[10:13]
	v_mfma_f32_16x16x32_bf16 v[62:65], v[182:185], v[214:217], v[62:65]
	v_mfma_f32_16x16x32_bf16 v[58:61], v[190:193], v[214:217], v[58:61]
	v_mfma_f32_16x16x32_bf16 v[50:53], v[182:185], v[230:233], v[50:53]
	v_mfma_f32_16x16x32_bf16 v[42:45], v[190:193], v[230:233], v[42:45]
	v_mfma_f32_16x16x32_bf16 v[34:37], v[182:185], v[238:241], v[34:37]
	v_mfma_f32_16x16x32_bf16 v[26:29], v[190:193], v[238:241], v[26:29]
	v_mfma_f32_16x16x32_bf16 v[18:21], v[182:185], v[246:249], v[18:21]
	v_mfma_f32_16x16x32_bf16 v[10:13], v[190:193], v[246:249], v[10:13]
	s_setprio 0
	s_setprio 1
	v_mfma_f32_16x16x32_bf16 v[54:57], v[194:197], v[210:213], v[54:57]
	v_mfma_f32_16x16x32_bf16 v[46:49], v[202:205], v[210:213], v[46:49]
	v_mfma_f32_16x16x32_bf16 v[38:41], v[194:197], v[226:229], v[38:41]
	v_mfma_f32_16x16x32_bf16 v[30:33], v[202:205], v[226:229], v[30:33]
	v_mfma_f32_16x16x32_bf16 v[22:25], v[194:197], v[234:237], v[22:25]
	v_mfma_f32_16x16x32_bf16 v[14:17], v[202:205], v[234:237], v[14:17]
	v_mfma_f32_16x16x32_bf16 v[6:9], v[194:197], v[242:245], v[6:9]
	v_mfma_f32_16x16x32_bf16 v[2:5], v[202:205], v[242:245], v[2:5]
	v_mfma_f32_16x16x32_bf16 v[54:57], v[198:201], v[214:217], v[54:57]
	v_mfma_f32_16x16x32_bf16 v[46:49], v[206:209], v[214:217], v[46:49]
	v_mfma_f32_16x16x32_bf16 v[38:41], v[198:201], v[230:233], v[38:41]
	v_mfma_f32_16x16x32_bf16 v[30:33], v[206:209], v[230:233], v[30:33]
	v_mfma_f32_16x16x32_bf16 v[22:25], v[198:201], v[238:241], v[22:25]
	v_mfma_f32_16x16x32_bf16 v[14:17], v[206:209], v[238:241], v[14:17]
	v_mfma_f32_16x16x32_bf16 v[6:9], v[198:201], v[246:249], v[6:9]
	v_mfma_f32_16x16x32_bf16 v[2:5], v[206:209], v[246:249], v[2:5]
	s_setprio 0
	s_barrier
	s_add_i32 s55, s55, 2
	s_add_u32 s53, s53, 0x100
	s_addc_u32 s54, s54, 0
	s_cmp_gt_u32 s55, 13
	s_cbranch_scc1 .LBB0_445
	s_mov_b64 s[4:5], s[22:23]
	s_branch .LBB0_439

.LBB0_692:
	s_ashr_i32 s17, s16, 31
	s_lshl_b64 s[18:19], s[16:17], 19
	s_add_u32 s18, s28, s18
	s_addc_u32 s19, s29, s19
	s_and_b64 s[20:21], s[6:7], exec
	s_cselect_b32 s17, s19, s23
	s_cselect_b32 s43, s18, s22
	s_ashr_i32 s15, s14, 31
	s_lshl_b64 s[20:21], s[14:15], 19
	s_add_u32 s20, s30, s20
	s_addc_u32 s21, s31, s21
	s_and_b64 s[26:27], s[6:7], exec
	s_cselect_b32 s15, s21, s25
	s_cselect_b32 s44, s20, s24
	s_add_u32 s22, s22, 0x40080
	s_addc_u32 s23, s23, 0
	s_add_u32 s45, s24, 0x100
	s_addc_u32 s46, s25, 0
	s_mov_b32 s47, -2
	s_waitcnt vmcnt(0)
	s_add_u32 s24, s22, 0xfffc0080
	s_addc_u32 s25, s23, -1
	s_add_i32 s48, 0, 0x10000
	s_cmp_eq_u32 s47, 12
	s_cselect_b32 s27, s17, s25
	s_cselect_b32 s26, s43, s24
	s_cselect_b32 s25, s15, s46
	s_cselect_b32 s24, s44, s45
	s_add_i32 s50, 0, 0x14000
	v_add_u32_e32 v134, s48, v191
	v_add_u32_e32 v158, s50, v191
	ds_read_b128 v[114:117], v134
	ds_read_b128 v[118:121], v134 offset:1024
	ds_read_b128 v[122:125], v134 offset:2048
	ds_read_b128 v[134:137], v134 offset:3072
	ds_read_b128 v[146:149], v158
	ds_read_b128 v[150:153], v158 offset:1024
	ds_read_b128 v[172:175], v158 offset:2048
	ds_read_b128 v[176:179], v158 offset:3072
	v_lshl_add_u64 v[158:159], s[22:23], 0, v[168:169]
	s_add_i32 m0, s34, 0xc000
	ds_read_b128 v[180:183], v193
	ds_read_b128 v[184:187], v193 offset:1024
	ds_read_b128 v[194:197], v193 offset:2048
	ds_read_b128 v[198:201], v193 offset:3072
	ds_read_b128 v[202:205], v193 offset:4096
	ds_read_b128 v[206:209], v193 offset:5120
	ds_read_b128 v[210:213], v193 offset:6144
	ds_read_b128 v[214:217], v193 offset:7168
	global_load_lds_dwordx4 v[158:159], off
	v_lshl_add_u64 v[158:159], s[22:23], 0, v[170:171]
	s_add_i32 m0, s34, 0xe000
	s_nop 0
	global_load_lds_dwordx4 v[158:159], off
	s_waitcnt vmcnt(8)
	s_waitcnt lgkmcnt(0)
	s_barrier
	s_setprio 1
	v_mfma_f32_16x16x32_bf16 v[142:145], v[114:117], v[180:183], 0
	v_mfma_f32_16x16x32_bf16 v[138:141], v[122:125], v[180:183], 0
	v_mfma_f32_16x16x32_bf16 v[110:113], v[114:117], v[194:197], 0
	v_mfma_f32_16x16x32_bf16 v[106:109], v[122:125], v[194:197], 0
	v_mfma_f32_16x16x32_bf16 v[94:97], v[114:117], v[202:205], 0
	v_mfma_f32_16x16x32_bf16 v[90:93], v[122:125], v[202:205], 0
	v_mfma_f32_16x16x32_bf16 v[78:81], v[114:117], v[210:213], 0
	v_mfma_f32_16x16x32_bf16 v[74:77], v[122:125], v[210:213], 0
	v_mfma_f32_16x16x32_bf16 v[142:145], v[118:121], v[184:187], v[142:145]
	v_mfma_f32_16x16x32_bf16 v[138:141], v[134:137], v[184:187], v[138:141]
	v_mfma_f32_16x16x32_bf16 v[110:113], v[118:121], v[198:201], v[110:113]
	v_mfma_f32_16x16x32_bf16 v[106:109], v[134:137], v[198:201], v[106:109]
	v_mfma_f32_16x16x32_bf16 v[94:97], v[118:121], v[206:209], v[94:97]
	v_mfma_f32_16x16x32_bf16 v[90:93], v[134:137], v[206:209], v[90:93]
	v_mfma_f32_16x16x32_bf16 v[78:81], v[118:121], v[214:217], v[78:81]
	v_mfma_f32_16x16x32_bf16 v[74:77], v[134:137], v[214:217], v[74:77]
	s_setprio 0
	s_setprio 1
	v_mfma_f32_16x16x32_bf16 v[130:133], v[146:149], v[180:183], 0
	v_mfma_f32_16x16x32_bf16 v[126:129], v[172:175], v[180:183], 0
	v_mfma_f32_16x16x32_bf16 v[102:105], v[146:149], v[194:197], 0
	v_mfma_f32_16x16x32_bf16 v[98:101], v[172:175], v[194:197], 0
	v_mfma_f32_16x16x32_bf16 v[86:89], v[146:149], v[202:205], 0
	v_mfma_f32_16x16x32_bf16 v[82:85], v[172:175], v[202:205], 0
	v_mfma_f32_16x16x32_bf16 v[70:73], v[146:149], v[210:213], 0
	v_mfma_f32_16x16x32_bf16 v[66:69], v[172:175], v[210:213], 0
	v_mfma_f32_16x16x32_bf16 v[130:133], v[150:153], v[184:187], v[130:133]
	v_mfma_f32_16x16x32_bf16 v[126:129], v[176:179], v[184:187], v[126:129]
	v_mfma_f32_16x16x32_bf16 v[102:105], v[150:153], v[198:201], v[102:105]
	v_mfma_f32_16x16x32_bf16 v[98:101], v[176:179], v[198:201], v[98:101]
	v_mfma_f32_16x16x32_bf16 v[86:89], v[150:153], v[206:209], v[86:89]
	v_mfma_f32_16x16x32_bf16 v[82:85], v[176:179], v[206:209], v[82:85]
	v_mfma_f32_16x16x32_bf16 v[70:73], v[150:153], v[214:217], v[70:73]
	v_mfma_f32_16x16x32_bf16 v[66:69], v[176:179], v[214:217], v[66:69]
	s_setprio 0
	s_barrier
	s_add_i32 s48, s48, s33
	v_lshl_add_u64 v[158:159], s[24:25], 0, v[0:1]
	s_mov_b32 m0, s48
	ds_read_b128 v[180:183], v193 offset:16384
	ds_read_b128 v[184:187], v193 offset:17408
	ds_read_b128 v[194:197], v193 offset:18432
	ds_read_b128 v[198:201], v193 offset:19456
	ds_read_b128 v[202:205], v193 offset:20480
	ds_read_b128 v[206:209], v193 offset:21504
	ds_read_b128 v[210:213], v193 offset:22528
	ds_read_b128 v[214:217], v193 offset:23552
	global_load_lds_dwordx4 v[158:159], off
	s_add_i32 m0, s48, 0x2000
	s_add_u32 s48, s24, 0x40000
	v_lshl_add_u64 v[162:163], s[24:25], 0, v[154:155]
	s_addc_u32 s49, s25, 0
	s_add_i32 s50, s50, s33
	global_load_lds_dwordx4 v[162:163], off
	v_lshl_add_u64 v[188:189], s[48:49], 0, v[0:1]
	s_mov_b32 m0, s50
	v_lshl_add_u64 v[218:219], s[26:27], 0, v[156:157]
	global_load_lds_dwordx4 v[188:189], off
	v_lshl_add_u64 v[188:189], s[48:49], 0, v[154:155]
	s_add_i32 m0, s50, 0x2000
	s_nop 0
	global_load_lds_dwordx4 v[188:189], off
	v_lshl_add_u64 v[188:189], s[26:27], 0, v[166:167]
	s_mov_b32 m0, s34
	s_nop 0
	global_load_lds_dwordx4 v[188:189], off
	s_mov_b32 m0, s35
	s_nop 0
	global_load_lds_dwordx4 v[218:219], off
	s_waitcnt vmcnt(8)
	s_waitcnt lgkmcnt(0)
	s_barrier
	s_setprio 1
	v_mfma_f32_16x16x32_bf16 v[62:65], v[114:117], v[180:183], 0
	v_mfma_f32_16x16x32_bf16 v[58:61], v[122:125], v[180:183], 0
	v_mfma_f32_16x16x32_bf16 v[46:49], v[114:117], v[194:197], 0
	v_mfma_f32_16x16x32_bf16 v[42:45], v[122:125], v[194:197], 0
	v_mfma_f32_16x16x32_bf16 v[30:33], v[114:117], v[202:205], 0
	v_mfma_f32_16x16x32_bf16 v[26:29], v[122:125], v[202:205], 0
	v_mfma_f32_16x16x32_bf16 v[14:17], v[114:117], v[210:213], 0
	v_mfma_f32_16x16x32_bf16 v[10:13], v[122:125], v[210:213], 0
	v_mfma_f32_16x16x32_bf16 v[62:65], v[118:121], v[184:187], v[62:65]
	v_mfma_f32_16x16x32_bf16 v[58:61], v[134:137], v[184:187], v[58:61]
	v_mfma_f32_16x16x32_bf16 v[46:49], v[118:121], v[198:201], v[46:49]
	v_mfma_f32_16x16x32_bf16 v[42:45], v[134:137], v[198:201], v[42:45]
	v_mfma_f32_16x16x32_bf16 v[30:33], v[118:121], v[206:209], v[30:33]
	v_mfma_f32_16x16x32_bf16 v[26:29], v[134:137], v[206:209], v[26:29]
	v_mfma_f32_16x16x32_bf16 v[14:17], v[118:121], v[214:217], v[14:17]
	v_mfma_f32_16x16x32_bf16 v[10:13], v[134:137], v[214:217], v[10:13]
	s_setprio 0
	s_setprio 1
	v_mfma_f32_16x16x32_bf16 v[54:57], v[146:149], v[180:183], 0
	v_mfma_f32_16x16x32_bf16 v[50:53], v[172:175], v[180:183], 0
	v_mfma_f32_16x16x32_bf16 v[38:41], v[146:149], v[194:197], 0
	v_mfma_f32_16x16x32_bf16 v[34:37], v[172:175], v[194:197], 0
	v_mfma_f32_16x16x32_bf16 v[22:25], v[146:149], v[202:205], 0
	v_mfma_f32_16x16x32_bf16 v[18:21], v[172:175], v[202:205], 0
	v_mfma_f32_16x16x32_bf16 v[6:9], v[146:149], v[210:213], 0
	v_mfma_f32_16x16x32_bf16 v[2:5], v[172:175], v[210:213], 0
	v_mfma_f32_16x16x32_bf16 v[54:57], v[150:153], v[184:187], v[54:57]
	v_mfma_f32_16x16x32_bf16 v[50:53], v[176:179], v[184:187], v[50:53]
	v_mfma_f32_16x16x32_bf16 v[38:41], v[150:153], v[198:201], v[38:41]
	v_mfma_f32_16x16x32_bf16 v[34:37], v[176:179], v[198:201], v[34:37]
	v_mfma_f32_16x16x32_bf16 v[22:25], v[150:153], v[206:209], v[22:25]
	v_mfma_f32_16x16x32_bf16 v[18:21], v[176:179], v[206:209], v[18:21]
	v_mfma_f32_16x16x32_bf16 v[6:9], v[150:153], v[214:217], v[6:9]
	v_mfma_f32_16x16x32_bf16 v[2:5], v[176:179], v[214:217], v[2:5]
	s_setprio 0
	s_barrier
	s_add_i32 s48, 0, 0x18000
	s_add_i32 s49, 0, 0x1c000
	v_add_u32_e32 v134, s48, v191
	v_add_u32_e32 v176, s49, v191
	ds_read_b128 v[114:117], v134
	ds_read_b128 v[118:121], v134 offset:1024
	ds_read_b128 v[122:125], v134 offset:2048
	ds_read_b128 v[134:137], v134 offset:3072
	ds_read_b128 v[146:149], v176
	ds_read_b128 v[150:153], v176 offset:1024
	ds_read_b128 v[172:175], v176 offset:2048
	ds_read_b128 v[176:179], v176 offset:3072
	s_add_u32 s26, s26, 0x40000
	s_addc_u32 s27, s27, 0
	s_mov_b32 m0, s36
	v_lshl_add_u64 v[220:221], s[26:27], 0, v[166:167]
	ds_read_b128 v[180:183], v193 offset:32768
	ds_read_b128 v[184:187], v193 offset:33792
	ds_read_b128 v[194:197], v193 offset:34816
	ds_read_b128 v[198:201], v193 offset:35840
	ds_read_b128 v[202:205], v193 offset:36864
	ds_read_b128 v[206:209], v193 offset:37888
	ds_read_b128 v[210:213], v193 offset:38912
	ds_read_b128 v[214:217], v193 offset:39936
	global_load_lds_dwordx4 v[220:221], off
	v_lshl_add_u64 v[220:221], s[26:27], 0, v[156:157]
	s_mov_b32 m0, s37
	s_nop 0
	global_load_lds_dwordx4 v[220:221], off
	s_waitcnt vmcnt(8)
	s_waitcnt lgkmcnt(0)
	s_barrier
	s_setprio 1
	v_mfma_f32_16x16x32_bf16 v[142:145], v[114:117], v[180:183], v[142:145]
	v_mfma_f32_16x16x32_bf16 v[138:141], v[122:125], v[180:183], v[138:141]
	v_mfma_f32_16x16x32_bf16 v[110:113], v[114:117], v[194:197], v[110:113]
	v_mfma_f32_16x16x32_bf16 v[106:109], v[122:125], v[194:197], v[106:109]
	v_mfma_f32_16x16x32_bf16 v[94:97], v[114:117], v[202:205], v[94:97]
	v_mfma_f32_16x16x32_bf16 v[90:93], v[122:125], v[202:205], v[90:93]
	v_mfma_f32_16x16x32_bf16 v[78:81], v[114:117], v[210:213], v[78:81]
	v_mfma_f32_16x16x32_bf16 v[74:77], v[122:125], v[210:213], v[74:77]
	v_mfma_f32_16x16x32_bf16 v[142:145], v[118:121], v[184:187], v[142:145]
	v_mfma_f32_16x16x32_bf16 v[138:141], v[134:137], v[184:187], v[138:141]
	v_mfma_f32_16x16x32_bf16 v[110:113], v[118:121], v[198:201], v[110:113]
	v_mfma_f32_16x16x32_bf16 v[106:109], v[134:137], v[198:201], v[106:109]
	v_mfma_f32_16x16x32_bf16 v[94:97], v[118:121], v[206:209], v[94:97]
	v_mfma_f32_16x16x32_bf16 v[90:93], v[134:137], v[206:209], v[90:93]
	v_mfma_f32_16x16x32_bf16 v[78:81], v[118:121], v[214:217], v[78:81]
	v_mfma_f32_16x16x32_bf16 v[74:77], v[134:137], v[214:217], v[74:77]
	s_setprio 0
	s_setprio 1
	v_mfma_f32_16x16x32_bf16 v[130:133], v[146:149], v[180:183], v[130:133]
	v_mfma_f32_16x16x32_bf16 v[126:129], v[172:175], v[180:183], v[126:129]
	v_mfma_f32_16x16x32_bf16 v[102:105], v[146:149], v[194:197], v[102:105]
	v_mfma_f32_16x16x32_bf16 v[98:101], v[172:175], v[194:197], v[98:101]
	v_mfma_f32_16x16x32_bf16 v[86:89], v[146:149], v[202:205], v[86:89]
	v_mfma_f32_16x16x32_bf16 v[82:85], v[172:175], v[202:205], v[82:85]
	v_mfma_f32_16x16x32_bf16 v[70:73], v[146:149], v[210:213], v[70:73]
	v_mfma_f32_16x16x32_bf16 v[66:69], v[172:175], v[210:213], v[66:69]
	v_mfma_f32_16x16x32_bf16 v[130:133], v[150:153], v[184:187], v[130:133]
	v_mfma_f32_16x16x32_bf16 v[126:129], v[176:179], v[184:187], v[126:129]
	v_mfma_f32_16x16x32_bf16 v[102:105], v[150:153], v[198:201], v[102:105]
	v_mfma_f32_16x16x32_bf16 v[98:101], v[176:179], v[198:201], v[98:101]
	v_mfma_f32_16x16x32_bf16 v[86:89], v[150:153], v[206:209], v[86:89]
	v_mfma_f32_16x16x32_bf16 v[82:85], v[176:179], v[206:209], v[82:85]
	v_mfma_f32_16x16x32_bf16 v[70:73], v[150:153], v[214:217], v[70:73]
	v_mfma_f32_16x16x32_bf16 v[66:69], v[176:179], v[214:217], v[66:69]
	s_setprio 0
	s_barrier
	s_add_i32 s26, s48, s33
	v_lshl_add_u64 v[158:159], v[158:159], 0, s[82:83]
	s_mov_b32 m0, s26
	ds_read_b128 v[180:183], v193 offset:49152
	ds_read_b128 v[184:187], v193 offset:50176
	ds_read_b128 v[194:197], v193 offset:51200
	ds_read_b128 v[198:201], v193 offset:52224
	ds_read_b128 v[202:205], v193 offset:53248
	ds_read_b128 v[206:209], v193 offset:54272
	ds_read_b128 v[210:213], v193 offset:55296
	ds_read_b128 v[214:217], v193 offset:56320
	global_load_lds_dwordx4 v[158:159], off
	s_add_i32 m0, s26, 0x2000
	s_add_u32 s24, s24, 0x40080
	v_lshl_add_u64 v[158:159], v[162:163], 0, s[82:83]
	s_addc_u32 s25, s25, 0
	s_add_i32 s26, s49, s33
	global_load_lds_dwordx4 v[158:159], off
	v_lshl_add_u64 v[158:159], s[24:25], 0, v[0:1]
	s_mov_b32 m0, s26
	s_nop 0
	global_load_lds_dwordx4 v[158:159], off
	v_lshl_add_u64 v[158:159], s[24:25], 0, v[154:155]
	s_add_i32 m0, s26, 0x2000
	s_nop 0
	global_load_lds_dwordx4 v[158:159], off
	v_lshl_add_u64 v[158:159], v[188:189], 0, s[82:83]
	s_mov_b32 m0, s38
	s_nop 0
	global_load_lds_dwordx4 v[158:159], off
	v_lshl_add_u64 v[158:159], v[218:219], 0, s[82:83]
	s_mov_b32 m0, s39
	s_nop 0
	global_load_lds_dwordx4 v[158:159], off
	s_waitcnt vmcnt(8)
	s_waitcnt lgkmcnt(0)
	s_barrier
	s_setprio 1
	v_mfma_f32_16x16x32_bf16 v[62:65], v[114:117], v[180:183], v[62:65]
	v_mfma_f32_16x16x32_bf16 v[58:61], v[122:125], v[180:183], v[58:61]
	v_mfma_f32_16x16x32_bf16 v[46:49], v[114:117], v[194:197], v[46:49]
	v_mfma_f32_16x16x32_bf16 v[42:45], v[122:125], v[194:197], v[42:45]
	v_mfma_f32_16x16x32_bf16 v[30:33], v[114:117], v[202:205], v[30:33]
	v_mfma_f32_16x16x32_bf16 v[26:29], v[122:125], v[202:205], v[26:29]
	v_mfma_f32_16x16x32_bf16 v[14:17], v[114:117], v[210:213], v[14:17]
	v_mfma_f32_16x16x32_bf16 v[10:13], v[122:125], v[210:213], v[10:13]
	v_mfma_f32_16x16x32_bf16 v[62:65], v[118:121], v[184:187], v[62:65]
	v_mfma_f32_16x16x32_bf16 v[58:61], v[134:137], v[184:187], v[58:61]
	v_mfma_f32_16x16x32_bf16 v[46:49], v[118:121], v[198:201], v[46:49]
	v_mfma_f32_16x16x32_bf16 v[42:45], v[134:137], v[198:201], v[42:45]
	v_mfma_f32_16x16x32_bf16 v[30:33], v[118:121], v[206:209], v[30:33]
	v_mfma_f32_16x16x32_bf16 v[26:29], v[134:137], v[206:209], v[26:29]
	v_mfma_f32_16x16x32_bf16 v[14:17], v[118:121], v[214:217], v[14:17]
	v_mfma_f32_16x16x32_bf16 v[10:13], v[134:137], v[214:217], v[10:13]
	s_setprio 0
	s_setprio 1
	v_mfma_f32_16x16x32_bf16 v[54:57], v[146:149], v[180:183], v[54:57]
	v_mfma_f32_16x16x32_bf16 v[50:53], v[172:175], v[180:183], v[50:53]
	v_mfma_f32_16x16x32_bf16 v[38:41], v[146:149], v[194:197], v[38:41]
	v_mfma_f32_16x16x32_bf16 v[34:37], v[172:175], v[194:197], v[34:37]
	v_mfma_f32_16x16x32_bf16 v[22:25], v[146:149], v[202:205], v[22:25]
	v_mfma_f32_16x16x32_bf16 v[18:21], v[172:175], v[202:205], v[18:21]
	v_mfma_f32_16x16x32_bf16 v[6:9], v[146:149], v[210:213], v[6:9]
	v_mfma_f32_16x16x32_bf16 v[2:5], v[172:175], v[210:213], v[2:5]
	v_mfma_f32_16x16x32_bf16 v[54:57], v[150:153], v[184:187], v[54:57]
	v_mfma_f32_16x16x32_bf16 v[50:53], v[176:179], v[184:187], v[50:53]
	v_mfma_f32_16x16x32_bf16 v[38:41], v[150:153], v[198:201], v[38:41]
	v_mfma_f32_16x16x32_bf16 v[34:37], v[176:179], v[198:201], v[34:37]
	v_mfma_f32_16x16x32_bf16 v[22:25], v[150:153], v[206:209], v[22:25]
	v_mfma_f32_16x16x32_bf16 v[18:21], v[176:179], v[206:209], v[18:21]
	v_mfma_f32_16x16x32_bf16 v[6:9], v[150:153], v[214:217], v[6:9]
	v_mfma_f32_16x16x32_bf16 v[2:5], v[176:179], v[214:217], v[2:5]
	s_setprio 0
	s_barrier
	s_add_i32 s47, s47, 2
	s_add_u32 s22, s22, 0x100
	s_addc_u32 s23, s23, 0
	s_add_u32 s45, s45, 0x100
	s_addc_u32 s46, s46, 0
	s_cmp_gt_u32 s47, 13
	s_cbranch_scc0 .LBB0_693

.LBB0_781:
	s_ashr_i32 s27, s26, 31
	s_lshl_b64 s[28:29], s[26:27], 19
	s_add_u32 s28, s46, s28
	s_addc_u32 s29, s47, s29
	s_and_b64 s[30:31], s[6:7], exec
	s_cselect_b32 s64, s29, s9
	s_cselect_b32 s65, s28, s8
	s_ashr_i32 s25, s24, 31
	s_lshl_b64 s[30:31], s[24:25], 19
	s_add_u32 s30, s49, s30
	s_addc_u32 s31, s50, s31
	s_and_b64 s[34:35], s[6:7], exec
	s_cselect_b32 s25, s31, s11
	s_cselect_b32 s66, s30, s10
	s_lshl_b32 s36, s24, 7
	s_lshl_b64 s[34:35], s[26:27], 10
	s_ashr_i32 s37, s36, 31
	s_add_u32 s27, s40, s34
	s_addc_u32 s67, s41, s35
	s_add_u32 s68, s10, 0x100
	s_addc_u32 s69, s11, 0
	s_mov_b32 s70, -2
	s_lshl_b64 s[10:11], s[36:37], 2
	s_cmp_eq_u32 s70, 12
	s_cselect_b64 s[36:37], -1, 0
	s_and_b64 s[34:35], s[6:7], s[36:37]
	s_andn2_b64 vcc, exec, s[34:35]
	s_cbranch_vccnz .Lpeel782_787
	v_mov_b32_e32 v0, v165
	s_nop 0
	v_readfirstlane_b32 s38, v0
	s_ashr_i32 s34, s38, 6
	s_and_b64 s[74:75], s[20:21], exec
	s_cselect_b32 s35, 0x1400, 0
	s_add_i32 s35, s35, 0
	v_and_b32_e32 v130, 63, v0
	s_add_i32 s35, s35, 0x20400
	s_cmp_gt_i32 s34, 3
	v_lshlrev_b32_e32 v0, 2, v130
	s_cbranch_scc1 .Lpeel782_785
	s_and_b32 s74, s38, 0xffffffc0
	s_lshl_b32 s39, s34, 8
	s_ashr_i32 s75, s74, 31
	s_add_i32 m0, s35, s39
	s_lshl_b64 s[74:75], s[74:75], 2
	s_add_u32 s74, s27, s74
	s_addc_u32 s75, s67, s75
	global_load_lds_dword v0, s[74:75]

.Lpeel782_787:
	s_add_u32 s34, s8, 0x100
	s_addc_u32 s35, s9, 0
	s_and_b64 s[36:37], s[36:37], exec
	s_cselect_b32 s39, s64, s35
	s_cselect_b32 s38, s65, s34
	s_cselect_b32 s37, s25, s69
	s_cselect_b32 s36, s66, s68
	s_add_i32 s71, 0, 0x10000
	v_add_u32_e32 v0, s71, v228
	s_add_i32 s74, 0, 0x14000
	ds_read_b128 v[130:133], v0
	ds_read_b128 v[134:137], v0 offset:1024
	ds_read_b128 v[138:141], v0 offset:2048
	ds_read_b128 v[154:157], v0 offset:3072
	v_add_u32_e32 v0, s74, v228
	ds_read_b128 v[166:169], v0
	ds_read_b128 v[170:173], v0 offset:1024
	ds_read_b128 v[174:177], v0 offset:2048
	ds_read_b128 v[178:181], v0 offset:3072
	v_lshl_add_u64 v[158:159], s[8:9], 0, v[150:151]
	s_add_i32 m0, s52, 0xc000
	ds_read_b128 v[182:185], v233
	ds_read_b128 v[186:189], v233 offset:1024
	ds_read_b128 v[190:193], v233 offset:2048
	ds_read_b128 v[194:197], v233 offset:3072
	ds_read_b128 v[198:201], v233 offset:4096
	ds_read_b128 v[202:205], v233 offset:5120
	ds_read_b128 v[206:209], v233 offset:6144
	ds_read_b128 v[210:213], v233 offset:7168
	global_load_lds_dwordx4 v[158:159], off
	v_lshl_add_u64 v[158:159], s[8:9], 0, v[152:153]
	s_add_i32 m0, s52, 0xe000
	s_nop 0
	global_load_lds_dwordx4 v[158:159], off
	s_waitcnt vmcnt(8)
	s_waitcnt lgkmcnt(0)
	s_barrier
	s_setprio 1
	v_mfma_f32_16x16x32_bf16 v[118:121], v[130:133], v[182:185], 0
	v_mfma_f32_16x16x32_bf16 v[54:57], v[138:141], v[182:185], 0
	v_mfma_f32_16x16x32_bf16 v[114:117], v[130:133], v[190:193], 0
	v_mfma_f32_16x16x32_bf16 v[50:53], v[138:141], v[190:193], 0
	v_mfma_f32_16x16x32_bf16 v[126:129], v[130:133], v[198:201], 0
	v_mfma_f32_16x16x32_bf16 v[62:65], v[138:141], v[198:201], 0
	v_mfma_f32_16x16x32_bf16 v[122:125], v[130:133], v[206:209], 0
	v_mfma_f32_16x16x32_bf16 v[58:61], v[138:141], v[206:209], 0
	v_mfma_f32_16x16x32_bf16 v[118:121], v[134:137], v[186:189], v[118:121]
	v_mfma_f32_16x16x32_bf16 v[54:57], v[154:157], v[186:189], v[54:57]
	v_mfma_f32_16x16x32_bf16 v[114:117], v[134:137], v[194:197], v[114:117]
	v_mfma_f32_16x16x32_bf16 v[50:53], v[154:157], v[194:197], v[50:53]
	v_mfma_f32_16x16x32_bf16 v[126:129], v[134:137], v[202:205], v[126:129]
	v_mfma_f32_16x16x32_bf16 v[62:65], v[154:157], v[202:205], v[62:65]
	v_mfma_f32_16x16x32_bf16 v[122:125], v[134:137], v[210:213], v[122:125]
	v_mfma_f32_16x16x32_bf16 v[58:61], v[154:157], v[210:213], v[58:61]
	s_setprio 0
	s_setprio 1
	v_mfma_f32_16x16x32_bf16 v[102:105], v[166:169], v[182:185], 0
	v_mfma_f32_16x16x32_bf16 v[38:41], v[174:177], v[182:185], 0
	v_mfma_f32_16x16x32_bf16 v[98:101], v[166:169], v[190:193], 0
	v_mfma_f32_16x16x32_bf16 v[34:37], v[174:177], v[190:193], 0
	v_mfma_f32_16x16x32_bf16 v[110:113], v[166:169], v[198:201], 0
	v_mfma_f32_16x16x32_bf16 v[46:49], v[174:177], v[198:201], 0
	v_mfma_f32_16x16x32_bf16 v[106:109], v[166:169], v[206:209], 0
	v_mfma_f32_16x16x32_bf16 v[42:45], v[174:177], v[206:209], 0
	v_mfma_f32_16x16x32_bf16 v[102:105], v[170:173], v[186:189], v[102:105]
	v_mfma_f32_16x16x32_bf16 v[38:41], v[178:181], v[186:189], v[38:41]
	v_mfma_f32_16x16x32_bf16 v[98:101], v[170:173], v[194:197], v[98:101]
	v_mfma_f32_16x16x32_bf16 v[34:37], v[178:181], v[194:197], v[34:37]
	v_mfma_f32_16x16x32_bf16 v[110:113], v[170:173], v[202:205], v[110:113]
	v_mfma_f32_16x16x32_bf16 v[46:49], v[178:181], v[202:205], v[46:49]
	v_mfma_f32_16x16x32_bf16 v[106:109], v[170:173], v[210:213], v[106:109]
	v_mfma_f32_16x16x32_bf16 v[42:45], v[178:181], v[210:213], v[42:45]
	s_setprio 0
	s_barrier
	s_add_i32 s8, s71, s51
	v_lshl_add_u64 v[158:159], s[36:37], 0, v[144:145]
	s_mov_b32 m0, s8
	ds_read_b128 v[182:185], v233 offset:16384
	ds_read_b128 v[186:189], v233 offset:17408
	ds_read_b128 v[190:193], v233 offset:18432
	ds_read_b128 v[194:197], v233 offset:19456
	ds_read_b128 v[198:201], v233 offset:20480
	ds_read_b128 v[202:205], v233 offset:21504
	ds_read_b128 v[206:209], v233 offset:22528
	ds_read_b128 v[210:213], v233 offset:23552
	global_load_lds_dwordx4 v[158:159], off
	s_add_i32 m0, s8, 0x2000
	s_add_u32 s8, s36, 0x40000
	v_lshl_add_u64 v[162:163], s[36:37], 0, v[148:149]
	s_addc_u32 s9, s37, 0
	s_add_i32 s71, s74, s51
	global_load_lds_dwordx4 v[162:163], off
	v_lshl_add_u64 v[214:215], s[8:9], 0, v[144:145]
	s_mov_b32 m0, s71
	v_lshl_add_u64 v[216:217], s[38:39], 0, v[146:147]
	global_load_lds_dwordx4 v[214:215], off
	v_lshl_add_u64 v[214:215], s[8:9], 0, v[148:149]
	s_add_i32 m0, s71, 0x2000
	s_nop 0
	global_load_lds_dwordx4 v[214:215], off
	v_lshl_add_u64 v[214:215], s[38:39], 0, v[142:143]
	s_mov_b32 m0, s52
	s_nop 0
	global_load_lds_dwordx4 v[214:215], off
	s_mov_b32 m0, s53
	s_nop 0
	global_load_lds_dwordx4 v[216:217], off
	s_waitcnt vmcnt(8)
	s_waitcnt lgkmcnt(0)
	s_barrier
	s_setprio 1
	v_mfma_f32_16x16x32_bf16 v[86:89], v[130:133], v[182:185], 0
	v_mfma_f32_16x16x32_bf16 v[22:25], v[138:141], v[182:185], 0
	v_mfma_f32_16x16x32_bf16 v[82:85], v[130:133], v[190:193], 0
	v_mfma_f32_16x16x32_bf16 v[18:21], v[138:141], v[190:193], 0
	v_mfma_f32_16x16x32_bf16 v[94:97], v[130:133], v[198:201], 0
	v_mfma_f32_16x16x32_bf16 v[30:33], v[138:141], v[198:201], 0
	v_mfma_f32_16x16x32_bf16 v[90:93], v[130:133], v[206:209], 0
	v_mfma_f32_16x16x32_bf16 v[26:29], v[138:141], v[206:209], 0
	v_mfma_f32_16x16x32_bf16 v[86:89], v[134:137], v[186:189], v[86:89]
	v_mfma_f32_16x16x32_bf16 v[22:25], v[154:157], v[186:189], v[22:25]
	v_mfma_f32_16x16x32_bf16 v[82:85], v[134:137], v[194:197], v[82:85]
	v_mfma_f32_16x16x32_bf16 v[18:21], v[154:157], v[194:197], v[18:21]
	v_mfma_f32_16x16x32_bf16 v[94:97], v[134:137], v[202:205], v[94:97]
	v_mfma_f32_16x16x32_bf16 v[30:33], v[154:157], v[202:205], v[30:33]
	v_mfma_f32_16x16x32_bf16 v[90:93], v[134:137], v[210:213], v[90:93]
	v_mfma_f32_16x16x32_bf16 v[26:29], v[154:157], v[210:213], v[26:29]
	s_setprio 0
	s_setprio 1
	v_mfma_f32_16x16x32_bf16 v[70:73], v[166:169], v[182:185], 0
	v_mfma_f32_16x16x32_bf16 v[6:9], v[174:177], v[182:185], 0
	v_mfma_f32_16x16x32_bf16 v[66:69], v[166:169], v[190:193], 0
	v_mfma_f32_16x16x32_bf16 v[2:5], v[174:177], v[190:193], 0
	v_mfma_f32_16x16x32_bf16 v[78:81], v[166:169], v[198:201], 0
	v_mfma_f32_16x16x32_bf16 v[14:17], v[174:177], v[198:201], 0
	v_mfma_f32_16x16x32_bf16 v[74:77], v[166:169], v[206:209], 0
	v_mfma_f32_16x16x32_bf16 v[10:13], v[174:177], v[206:209], 0
	v_mfma_f32_16x16x32_bf16 v[70:73], v[170:173], v[186:189], v[70:73]
	v_mfma_f32_16x16x32_bf16 v[6:9], v[178:181], v[186:189], v[6:9]
	v_mfma_f32_16x16x32_bf16 v[66:69], v[170:173], v[194:197], v[66:69]
	v_mfma_f32_16x16x32_bf16 v[2:5], v[178:181], v[194:197], v[2:5]
	v_mfma_f32_16x16x32_bf16 v[78:81], v[170:173], v[202:205], v[78:81]
	v_mfma_f32_16x16x32_bf16 v[14:17], v[178:181], v[202:205], v[14:17]
	v_mfma_f32_16x16x32_bf16 v[74:77], v[170:173], v[210:213], v[74:77]
	v_mfma_f32_16x16x32_bf16 v[10:13], v[178:181], v[210:213], v[10:13]
	s_setprio 0
	s_barrier
	s_add_i32 s71, 0, 0x18000
	v_add_u32_e32 v0, s71, v228
	s_add_i32 s74, 0, 0x1c000
	ds_read_b128 v[130:133], v0
	ds_read_b128 v[134:137], v0 offset:1024
	ds_read_b128 v[138:141], v0 offset:2048
	ds_read_b128 v[154:157], v0 offset:3072
	v_add_u32_e32 v0, s74, v228
	ds_read_b128 v[166:169], v0
	ds_read_b128 v[170:173], v0 offset:1024
	ds_read_b128 v[174:177], v0 offset:2048
	ds_read_b128 v[178:181], v0 offset:3072
	s_add_u32 s8, s38, 0x40000
	s_addc_u32 s9, s39, 0
	s_mov_b32 m0, s54
	v_lshl_add_u64 v[218:219], s[8:9], 0, v[142:143]
	ds_read_b128 v[182:185], v233 offset:32768
	ds_read_b128 v[186:189], v233 offset:33792
	ds_read_b128 v[190:193], v233 offset:34816
	ds_read_b128 v[194:197], v233 offset:35840
	ds_read_b128 v[198:201], v233 offset:36864
	ds_read_b128 v[202:205], v233 offset:37888
	ds_read_b128 v[206:209], v233 offset:38912
	ds_read_b128 v[210:213], v233 offset:39936
	global_load_lds_dwordx4 v[218:219], off
	v_lshl_add_u64 v[218:219], s[8:9], 0, v[146:147]
	s_mov_b32 m0, s55
	s_nop 0
	global_load_lds_dwordx4 v[218:219], off
	s_waitcnt vmcnt(8)
	s_waitcnt lgkmcnt(0)
	s_barrier
	s_setprio 1
	v_mfma_f32_16x16x32_bf16 v[118:121], v[130:133], v[182:185], v[118:121]
	v_mfma_f32_16x16x32_bf16 v[54:57], v[138:141], v[182:185], v[54:57]
	v_mfma_f32_16x16x32_bf16 v[114:117], v[130:133], v[190:193], v[114:117]
	v_mfma_f32_16x16x32_bf16 v[50:53], v[138:141], v[190:193], v[50:53]
	v_mfma_f32_16x16x32_bf16 v[126:129], v[130:133], v[198:201], v[126:129]
	v_mfma_f32_16x16x32_bf16 v[62:65], v[138:141], v[198:201], v[62:65]
	v_mfma_f32_16x16x32_bf16 v[122:125], v[130:133], v[206:209], v[122:125]
	v_mfma_f32_16x16x32_bf16 v[58:61], v[138:141], v[206:209], v[58:61]
	v_mfma_f32_16x16x32_bf16 v[118:121], v[134:137], v[186:189], v[118:121]
	v_mfma_f32_16x16x32_bf16 v[54:57], v[154:157], v[186:189], v[54:57]
	v_mfma_f32_16x16x32_bf16 v[114:117], v[134:137], v[194:197], v[114:117]
	v_mfma_f32_16x16x32_bf16 v[50:53], v[154:157], v[194:197], v[50:53]
	v_mfma_f32_16x16x32_bf16 v[126:129], v[134:137], v[202:205], v[126:129]
	v_mfma_f32_16x16x32_bf16 v[62:65], v[154:157], v[202:205], v[62:65]
	v_mfma_f32_16x16x32_bf16 v[122:125], v[134:137], v[210:213], v[122:125]
	v_mfma_f32_16x16x32_bf16 v[58:61], v[154:157], v[210:213], v[58:61]
	s_setprio 0
	s_setprio 1
	v_mfma_f32_16x16x32_bf16 v[102:105], v[166:169], v[182:185], v[102:105]
	v_mfma_f32_16x16x32_bf16 v[38:41], v[174:177], v[182:185], v[38:41]
	v_mfma_f32_16x16x32_bf16 v[98:101], v[166:169], v[190:193], v[98:101]
	v_mfma_f32_16x16x32_bf16 v[34:37], v[174:177], v[190:193], v[34:37]
	v_mfma_f32_16x16x32_bf16 v[110:113], v[166:169], v[198:201], v[110:113]
	v_mfma_f32_16x16x32_bf16 v[46:49], v[174:177], v[198:201], v[46:49]
	v_mfma_f32_16x16x32_bf16 v[106:109], v[166:169], v[206:209], v[106:109]
	v_mfma_f32_16x16x32_bf16 v[42:45], v[174:177], v[206:209], v[42:45]
	v_mfma_f32_16x16x32_bf16 v[102:105], v[170:173], v[186:189], v[102:105]
	v_mfma_f32_16x16x32_bf16 v[38:41], v[178:181], v[186:189], v[38:41]
	v_mfma_f32_16x16x32_bf16 v[98:101], v[170:173], v[194:197], v[98:101]
	v_mfma_f32_16x16x32_bf16 v[34:37], v[178:181], v[194:197], v[34:37]
	v_mfma_f32_16x16x32_bf16 v[110:113], v[170:173], v[202:205], v[110:113]
	v_mfma_f32_16x16x32_bf16 v[46:49], v[178:181], v[202:205], v[46:49]
	v_mfma_f32_16x16x32_bf16 v[106:109], v[170:173], v[210:213], v[106:109]
	v_mfma_f32_16x16x32_bf16 v[42:45], v[178:181], v[210:213], v[42:45]
	s_setprio 0
	s_barrier
	s_add_i32 s8, s71, s51
	v_lshl_add_u64 v[158:159], v[158:159], 0, s[82:83]
	s_mov_b32 m0, s8
	ds_read_b128 v[182:185], v233 offset:49152
	ds_read_b128 v[186:189], v233 offset:50176
	ds_read_b128 v[190:193], v233 offset:51200
	ds_read_b128 v[194:197], v233 offset:52224
	ds_read_b128 v[198:201], v233 offset:53248
	ds_read_b128 v[202:205], v233 offset:54272
	ds_read_b128 v[206:209], v233 offset:55296
	ds_read_b128 v[210:213], v233 offset:56320
	global_load_lds_dwordx4 v[158:159], off
	s_add_i32 m0, s8, 0x2000
	s_add_u32 s8, s36, 0x40080
	v_lshl_add_u64 v[158:159], v[162:163], 0, s[82:83]
	s_addc_u32 s9, s37, 0
	s_add_i32 s36, s74, s51
	global_load_lds_dwordx4 v[158:159], off
	v_lshl_add_u64 v[158:159], s[8:9], 0, v[144:145]
	s_mov_b32 m0, s36
	s_nop 0
	global_load_lds_dwordx4 v[158:159], off
	v_lshl_add_u64 v[158:159], s[8:9], 0, v[148:149]
	s_add_i32 m0, s36, 0x2000
	s_nop 0
	global_load_lds_dwordx4 v[158:159], off
	v_lshl_add_u64 v[158:159], v[214:215], 0, s[82:83]
	s_mov_b32 m0, s58
	s_nop 0
	global_load_lds_dwordx4 v[158:159], off
	v_lshl_add_u64 v[158:159], v[216:217], 0, s[82:83]
	s_mov_b32 m0, s59
	s_nop 0
	global_load_lds_dwordx4 v[158:159], off
	s_waitcnt vmcnt(8)
	s_waitcnt lgkmcnt(0)
	s_barrier
	s_setprio 1
	v_mfma_f32_16x16x32_bf16 v[86:89], v[130:133], v[182:185], v[86:89]
	v_mfma_f32_16x16x32_bf16 v[22:25], v[138:141], v[182:185], v[22:25]
	v_mfma_f32_16x16x32_bf16 v[82:85], v[130:133], v[190:193], v[82:85]
	v_mfma_f32_16x16x32_bf16 v[18:21], v[138:141], v[190:193], v[18:21]
	v_mfma_f32_16x16x32_bf16 v[94:97], v[130:133], v[198:201], v[94:97]
	v_mfma_f32_16x16x32_bf16 v[30:33], v[138:141], v[198:201], v[30:33]
	v_mfma_f32_16x16x32_bf16 v[90:93], v[130:133], v[206:209], v[90:93]
	v_mfma_f32_16x16x32_bf16 v[26:29], v[138:141], v[206:209], v[26:29]
	v_mfma_f32_16x16x32_bf16 v[86:89], v[134:137], v[186:189], v[86:89]
	v_mfma_f32_16x16x32_bf16 v[22:25], v[154:157], v[186:189], v[22:25]
	v_mfma_f32_16x16x32_bf16 v[82:85], v[134:137], v[194:197], v[82:85]
	v_mfma_f32_16x16x32_bf16 v[18:21], v[154:157], v[194:197], v[18:21]
	v_mfma_f32_16x16x32_bf16 v[94:97], v[134:137], v[202:205], v[94:97]
	v_mfma_f32_16x16x32_bf16 v[30:33], v[154:157], v[202:205], v[30:33]
	v_mfma_f32_16x16x32_bf16 v[90:93], v[134:137], v[210:213], v[90:93]
	v_mfma_f32_16x16x32_bf16 v[26:29], v[154:157], v[210:213], v[26:29]
	s_setprio 0
	s_setprio 1
	v_mfma_f32_16x16x32_bf16 v[70:73], v[166:169], v[182:185], v[70:73]
	v_mfma_f32_16x16x32_bf16 v[6:9], v[174:177], v[182:185], v[6:9]
	v_mfma_f32_16x16x32_bf16 v[66:69], v[166:169], v[190:193], v[66:69]
	v_mfma_f32_16x16x32_bf16 v[2:5], v[174:177], v[190:193], v[2:5]
	v_mfma_f32_16x16x32_bf16 v[78:81], v[166:169], v[198:201], v[78:81]
	v_mfma_f32_16x16x32_bf16 v[14:17], v[174:177], v[198:201], v[14:17]
	v_mfma_f32_16x16x32_bf16 v[74:77], v[166:169], v[206:209], v[74:77]
	v_mfma_f32_16x16x32_bf16 v[10:13], v[174:177], v[206:209], v[10:13]
	v_mfma_f32_16x16x32_bf16 v[70:73], v[170:173], v[186:189], v[70:73]
	v_mfma_f32_16x16x32_bf16 v[6:9], v[178:181], v[186:189], v[6:9]
	v_mfma_f32_16x16x32_bf16 v[66:69], v[170:173], v[194:197], v[66:69]
	v_mfma_f32_16x16x32_bf16 v[2:5], v[178:181], v[194:197], v[2:5]
	v_mfma_f32_16x16x32_bf16 v[78:81], v[170:173], v[202:205], v[78:81]
	v_mfma_f32_16x16x32_bf16 v[14:17], v[178:181], v[202:205], v[14:17]
	v_mfma_f32_16x16x32_bf16 v[74:77], v[170:173], v[210:213], v[74:77]
	v_mfma_f32_16x16x32_bf16 v[10:13], v[178:181], v[210:213], v[10:13]
	s_setprio 0
	s_barrier
	s_add_i32 s70, s70, 2
	s_add_u32 s68, s68, 0x100
	s_addc_u32 s69, s69, 0
	s_cmp_gt_u32 s70, 13
	s_cbranch_scc1 .LBB0_789
	s_mov_b64 s[8:9], s[34:35]
	s_branch .LBB0_782

.LBB0_965:
	s_add_u32 s43, s20, 0x100
	s_addc_u32 s44, s21, 0
	s_mov_b32 s45, -2
	s_add_u32 s20, s18, 0x100
	s_addc_u32 s21, s19, 0
	s_add_i32 s46, 0, 0x10000
	s_cmp_eq_u32 s45, 40
	s_cselect_b32 s25, s9, s21
	s_cselect_b32 s24, s8, s20
	s_cselect_b32 s23, s17, s44
	s_cselect_b32 s22, s16, s43
	s_add_i32 s47, 0, 0x14000
	v_add_u32_e32 v134, s46, v191
	v_add_u32_e32 v158, s47, v191
	ds_read_b128 v[114:117], v134
	ds_read_b128 v[118:121], v134 offset:1024
	ds_read_b128 v[122:125], v134 offset:2048
	ds_read_b128 v[134:137], v134 offset:3072
	ds_read_b128 v[146:149], v158
	ds_read_b128 v[150:153], v158 offset:1024
	ds_read_b128 v[172:175], v158 offset:2048
	ds_read_b128 v[176:179], v158 offset:3072
	v_lshl_add_u64 v[158:159], s[18:19], 0, v[168:169]
	s_add_i32 m0, s31, 0xc000
	ds_read_b128 v[180:183], v193
	ds_read_b128 v[184:187], v193 offset:1024
	ds_read_b128 v[194:197], v193 offset:2048
	ds_read_b128 v[198:201], v193 offset:3072
	ds_read_b128 v[202:205], v193 offset:4096
	ds_read_b128 v[206:209], v193 offset:5120
	ds_read_b128 v[210:213], v193 offset:6144
	ds_read_b128 v[214:217], v193 offset:7168
	global_load_lds_dwordx4 v[158:159], off
	v_lshl_add_u64 v[158:159], s[18:19], 0, v[170:171]
	s_add_i32 m0, s31, 0xe000
	s_nop 0
	global_load_lds_dwordx4 v[158:159], off
	s_waitcnt vmcnt(8)
	s_waitcnt lgkmcnt(0)
	s_barrier
	s_setprio 1
	v_mfma_f32_16x16x32_bf16 v[142:145], v[114:117], v[180:183], 0
	v_mfma_f32_16x16x32_bf16 v[138:141], v[122:125], v[180:183], 0
	v_mfma_f32_16x16x32_bf16 v[110:113], v[114:117], v[194:197], 0
	v_mfma_f32_16x16x32_bf16 v[106:109], v[122:125], v[194:197], 0
	v_mfma_f32_16x16x32_bf16 v[94:97], v[114:117], v[202:205], 0
	v_mfma_f32_16x16x32_bf16 v[90:93], v[122:125], v[202:205], 0
	v_mfma_f32_16x16x32_bf16 v[78:81], v[114:117], v[210:213], 0
	v_mfma_f32_16x16x32_bf16 v[74:77], v[122:125], v[210:213], 0
	v_mfma_f32_16x16x32_bf16 v[142:145], v[118:121], v[184:187], v[142:145]
	v_mfma_f32_16x16x32_bf16 v[138:141], v[134:137], v[184:187], v[138:141]
	v_mfma_f32_16x16x32_bf16 v[110:113], v[118:121], v[198:201], v[110:113]
	v_mfma_f32_16x16x32_bf16 v[106:109], v[134:137], v[198:201], v[106:109]
	v_mfma_f32_16x16x32_bf16 v[94:97], v[118:121], v[206:209], v[94:97]
	v_mfma_f32_16x16x32_bf16 v[90:93], v[134:137], v[206:209], v[90:93]
	v_mfma_f32_16x16x32_bf16 v[78:81], v[118:121], v[214:217], v[78:81]
	v_mfma_f32_16x16x32_bf16 v[74:77], v[134:137], v[214:217], v[74:77]
	s_setprio 0
	s_setprio 1
	v_mfma_f32_16x16x32_bf16 v[130:133], v[146:149], v[180:183], 0
	v_mfma_f32_16x16x32_bf16 v[126:129], v[172:175], v[180:183], 0
	v_mfma_f32_16x16x32_bf16 v[102:105], v[146:149], v[194:197], 0
	v_mfma_f32_16x16x32_bf16 v[98:101], v[172:175], v[194:197], 0
	v_mfma_f32_16x16x32_bf16 v[86:89], v[146:149], v[202:205], 0
	v_mfma_f32_16x16x32_bf16 v[82:85], v[172:175], v[202:205], 0
	v_mfma_f32_16x16x32_bf16 v[70:73], v[146:149], v[210:213], 0
	v_mfma_f32_16x16x32_bf16 v[66:69], v[172:175], v[210:213], 0
	v_mfma_f32_16x16x32_bf16 v[130:133], v[150:153], v[184:187], v[130:133]
	v_mfma_f32_16x16x32_bf16 v[126:129], v[176:179], v[184:187], v[126:129]
	v_mfma_f32_16x16x32_bf16 v[102:105], v[150:153], v[198:201], v[102:105]
	v_mfma_f32_16x16x32_bf16 v[98:101], v[176:179], v[198:201], v[98:101]
	v_mfma_f32_16x16x32_bf16 v[86:89], v[150:153], v[206:209], v[86:89]
	v_mfma_f32_16x16x32_bf16 v[82:85], v[176:179], v[206:209], v[82:85]
	v_mfma_f32_16x16x32_bf16 v[70:73], v[150:153], v[214:217], v[70:73]
	v_mfma_f32_16x16x32_bf16 v[66:69], v[176:179], v[214:217], v[66:69]
	s_setprio 0
	s_barrier
	s_add_i32 s18, s46, s30
	v_lshl_add_u64 v[158:159], s[22:23], 0, v[0:1]
	s_mov_b32 m0, s18
	ds_read_b128 v[180:183], v193 offset:16384
	ds_read_b128 v[184:187], v193 offset:17408
	ds_read_b128 v[194:197], v193 offset:18432
	ds_read_b128 v[198:201], v193 offset:19456
	ds_read_b128 v[202:205], v193 offset:20480
	ds_read_b128 v[206:209], v193 offset:21504
	ds_read_b128 v[210:213], v193 offset:22528
	ds_read_b128 v[214:217], v193 offset:23552
	global_load_lds_dwordx4 v[158:159], off
	s_add_i32 m0, s18, 0x2000
	s_add_u32 s18, s22, 0xb0000
	v_lshl_add_u64 v[162:163], s[22:23], 0, v[154:155]
	s_addc_u32 s19, s23, 0
	s_add_i32 s46, s47, s30
	global_load_lds_dwordx4 v[162:163], off
	v_lshl_add_u64 v[188:189], s[18:19], 0, v[0:1]
	s_mov_b32 m0, s46
	v_lshl_add_u64 v[218:219], s[24:25], 0, v[156:157]
	global_load_lds_dwordx4 v[188:189], off
	v_lshl_add_u64 v[188:189], s[18:19], 0, v[154:155]
	s_add_i32 m0, s46, 0x2000
	s_nop 0
	global_load_lds_dwordx4 v[188:189], off
	v_lshl_add_u64 v[188:189], s[24:25], 0, v[166:167]
	s_mov_b32 m0, s31
	s_nop 0
	global_load_lds_dwordx4 v[188:189], off
	s_mov_b32 m0, s33
	s_nop 0
	global_load_lds_dwordx4 v[218:219], off
	s_waitcnt vmcnt(8)
	s_waitcnt lgkmcnt(0)
	s_barrier
	s_setprio 1
	v_mfma_f32_16x16x32_bf16 v[62:65], v[114:117], v[180:183], 0
	v_mfma_f32_16x16x32_bf16 v[58:61], v[122:125], v[180:183], 0
	v_mfma_f32_16x16x32_bf16 v[46:49], v[114:117], v[194:197], 0
	v_mfma_f32_16x16x32_bf16 v[42:45], v[122:125], v[194:197], 0
	v_mfma_f32_16x16x32_bf16 v[30:33], v[114:117], v[202:205], 0
	v_mfma_f32_16x16x32_bf16 v[26:29], v[122:125], v[202:205], 0
	v_mfma_f32_16x16x32_bf16 v[14:17], v[114:117], v[210:213], 0
	v_mfma_f32_16x16x32_bf16 v[10:13], v[122:125], v[210:213], 0
	v_mfma_f32_16x16x32_bf16 v[62:65], v[118:121], v[184:187], v[62:65]
	v_mfma_f32_16x16x32_bf16 v[58:61], v[134:137], v[184:187], v[58:61]
	v_mfma_f32_16x16x32_bf16 v[46:49], v[118:121], v[198:201], v[46:49]
	v_mfma_f32_16x16x32_bf16 v[42:45], v[134:137], v[198:201], v[42:45]
	v_mfma_f32_16x16x32_bf16 v[30:33], v[118:121], v[206:209], v[30:33]
	v_mfma_f32_16x16x32_bf16 v[26:29], v[134:137], v[206:209], v[26:29]
	v_mfma_f32_16x16x32_bf16 v[14:17], v[118:121], v[214:217], v[14:17]
	v_mfma_f32_16x16x32_bf16 v[10:13], v[134:137], v[214:217], v[10:13]
	s_setprio 0
	s_setprio 1
	v_mfma_f32_16x16x32_bf16 v[54:57], v[146:149], v[180:183], 0
	v_mfma_f32_16x16x32_bf16 v[50:53], v[172:175], v[180:183], 0
	v_mfma_f32_16x16x32_bf16 v[38:41], v[146:149], v[194:197], 0
	v_mfma_f32_16x16x32_bf16 v[34:37], v[172:175], v[194:197], 0
	v_mfma_f32_16x16x32_bf16 v[22:25], v[146:149], v[202:205], 0
	v_mfma_f32_16x16x32_bf16 v[18:21], v[172:175], v[202:205], 0
	v_mfma_f32_16x16x32_bf16 v[6:9], v[146:149], v[210:213], 0
	v_mfma_f32_16x16x32_bf16 v[2:5], v[172:175], v[210:213], 0
	v_mfma_f32_16x16x32_bf16 v[54:57], v[150:153], v[184:187], v[54:57]
	v_mfma_f32_16x16x32_bf16 v[50:53], v[176:179], v[184:187], v[50:53]
	v_mfma_f32_16x16x32_bf16 v[38:41], v[150:153], v[198:201], v[38:41]
	v_mfma_f32_16x16x32_bf16 v[34:37], v[176:179], v[198:201], v[34:37]
	v_mfma_f32_16x16x32_bf16 v[22:25], v[150:153], v[206:209], v[22:25]
	v_mfma_f32_16x16x32_bf16 v[18:21], v[176:179], v[206:209], v[18:21]
	v_mfma_f32_16x16x32_bf16 v[6:9], v[150:153], v[214:217], v[6:9]
	v_mfma_f32_16x16x32_bf16 v[2:5], v[176:179], v[214:217], v[2:5]
	s_setprio 0
	s_barrier
	s_add_i32 s46, 0, 0x18000
	s_add_i32 s47, 0, 0x1c000
	v_add_u32_e32 v134, s46, v191
	v_add_u32_e32 v176, s47, v191
	ds_read_b128 v[114:117], v134
	ds_read_b128 v[118:121], v134 offset:1024
	ds_read_b128 v[122:125], v134 offset:2048
	ds_read_b128 v[134:137], v134 offset:3072
	ds_read_b128 v[146:149], v176
	ds_read_b128 v[150:153], v176 offset:1024
	ds_read_b128 v[172:175], v176 offset:2048
	ds_read_b128 v[176:179], v176 offset:3072
	s_add_u32 s18, s24, 0xb0000
	s_addc_u32 s19, s25, 0
	s_mov_b32 m0, s34
	v_lshl_add_u64 v[220:221], s[18:19], 0, v[166:167]
	ds_read_b128 v[180:183], v193 offset:32768
	ds_read_b128 v[184:187], v193 offset:33792
	ds_read_b128 v[194:197], v193 offset:34816
	ds_read_b128 v[198:201], v193 offset:35840
	ds_read_b128 v[202:205], v193 offset:36864
	ds_read_b128 v[206:209], v193 offset:37888
	ds_read_b128 v[210:213], v193 offset:38912
	ds_read_b128 v[214:217], v193 offset:39936
	global_load_lds_dwordx4 v[220:221], off
	v_lshl_add_u64 v[220:221], s[18:19], 0, v[156:157]
	s_mov_b32 m0, s35
	s_nop 0
	global_load_lds_dwordx4 v[220:221], off
	s_waitcnt vmcnt(8)
	s_waitcnt lgkmcnt(0)
	s_barrier
	s_setprio 1
	v_mfma_f32_16x16x32_bf16 v[142:145], v[114:117], v[180:183], v[142:145]
	v_mfma_f32_16x16x32_bf16 v[138:141], v[122:125], v[180:183], v[138:141]
	v_mfma_f32_16x16x32_bf16 v[110:113], v[114:117], v[194:197], v[110:113]
	v_mfma_f32_16x16x32_bf16 v[106:109], v[122:125], v[194:197], v[106:109]
	v_mfma_f32_16x16x32_bf16 v[94:97], v[114:117], v[202:205], v[94:97]
	v_mfma_f32_16x16x32_bf16 v[90:93], v[122:125], v[202:205], v[90:93]
	v_mfma_f32_16x16x32_bf16 v[78:81], v[114:117], v[210:213], v[78:81]
	v_mfma_f32_16x16x32_bf16 v[74:77], v[122:125], v[210:213], v[74:77]
	v_mfma_f32_16x16x32_bf16 v[142:145], v[118:121], v[184:187], v[142:145]
	v_mfma_f32_16x16x32_bf16 v[138:141], v[134:137], v[184:187], v[138:141]
	v_mfma_f32_16x16x32_bf16 v[110:113], v[118:121], v[198:201], v[110:113]
	v_mfma_f32_16x16x32_bf16 v[106:109], v[134:137], v[198:201], v[106:109]
	v_mfma_f32_16x16x32_bf16 v[94:97], v[118:121], v[206:209], v[94:97]
	v_mfma_f32_16x16x32_bf16 v[90:93], v[134:137], v[206:209], v[90:93]
	v_mfma_f32_16x16x32_bf16 v[78:81], v[118:121], v[214:217], v[78:81]
	v_mfma_f32_16x16x32_bf16 v[74:77], v[134:137], v[214:217], v[74:77]
	s_setprio 0
	s_setprio 1
	v_mfma_f32_16x16x32_bf16 v[130:133], v[146:149], v[180:183], v[130:133]
	v_mfma_f32_16x16x32_bf16 v[126:129], v[172:175], v[180:183], v[126:129]
	v_mfma_f32_16x16x32_bf16 v[102:105], v[146:149], v[194:197], v[102:105]
	v_mfma_f32_16x16x32_bf16 v[98:101], v[172:175], v[194:197], v[98:101]
	v_mfma_f32_16x16x32_bf16 v[86:89], v[146:149], v[202:205], v[86:89]
	v_mfma_f32_16x16x32_bf16 v[82:85], v[172:175], v[202:205], v[82:85]
	v_mfma_f32_16x16x32_bf16 v[70:73], v[146:149], v[210:213], v[70:73]
	v_mfma_f32_16x16x32_bf16 v[66:69], v[172:175], v[210:213], v[66:69]
	v_mfma_f32_16x16x32_bf16 v[130:133], v[150:153], v[184:187], v[130:133]
	v_mfma_f32_16x16x32_bf16 v[126:129], v[176:179], v[184:187], v[126:129]
	v_mfma_f32_16x16x32_bf16 v[102:105], v[150:153], v[198:201], v[102:105]
	v_mfma_f32_16x16x32_bf16 v[98:101], v[176:179], v[198:201], v[98:101]
	v_mfma_f32_16x16x32_bf16 v[86:89], v[150:153], v[206:209], v[86:89]
	v_mfma_f32_16x16x32_bf16 v[82:85], v[176:179], v[206:209], v[82:85]
	v_mfma_f32_16x16x32_bf16 v[70:73], v[150:153], v[214:217], v[70:73]
	v_mfma_f32_16x16x32_bf16 v[66:69], v[176:179], v[214:217], v[66:69]
	s_setprio 0
	s_barrier
	s_add_i32 s18, s46, s30
	v_lshl_add_u64 v[158:159], v[158:159], 0, s[82:83]
	s_mov_b32 m0, s18
	ds_read_b128 v[180:183], v193 offset:49152
	ds_read_b128 v[184:187], v193 offset:50176
	ds_read_b128 v[194:197], v193 offset:51200
	ds_read_b128 v[198:201], v193 offset:52224
	ds_read_b128 v[202:205], v193 offset:53248
	ds_read_b128 v[206:209], v193 offset:54272
	ds_read_b128 v[210:213], v193 offset:55296
	ds_read_b128 v[214:217], v193 offset:56320
	global_load_lds_dwordx4 v[158:159], off
	s_add_i32 m0, s18, 0x2000
	s_add_u32 s18, s22, 0xb0080
	v_lshl_add_u64 v[158:159], v[162:163], 0, s[82:83]
	s_addc_u32 s19, s23, 0
	s_add_i32 s22, s47, s30
	global_load_lds_dwordx4 v[158:159], off
	v_lshl_add_u64 v[158:159], s[18:19], 0, v[0:1]
	s_mov_b32 m0, s22
	s_nop 0
	global_load_lds_dwordx4 v[158:159], off
	v_lshl_add_u64 v[158:159], s[18:19], 0, v[154:155]
	s_add_i32 m0, s22, 0x2000
	s_nop 0
	global_load_lds_dwordx4 v[158:159], off
	v_lshl_add_u64 v[158:159], v[188:189], 0, s[82:83]
	s_mov_b32 m0, s36
	s_nop 0
	global_load_lds_dwordx4 v[158:159], off
	v_lshl_add_u64 v[158:159], v[218:219], 0, s[82:83]
	s_mov_b32 m0, s37
	s_nop 0
	global_load_lds_dwordx4 v[158:159], off
	s_waitcnt vmcnt(8)
	s_waitcnt lgkmcnt(0)
	s_barrier
	s_setprio 1
	v_mfma_f32_16x16x32_bf16 v[62:65], v[114:117], v[180:183], v[62:65]
	v_mfma_f32_16x16x32_bf16 v[58:61], v[122:125], v[180:183], v[58:61]
	v_mfma_f32_16x16x32_bf16 v[46:49], v[114:117], v[194:197], v[46:49]
	v_mfma_f32_16x16x32_bf16 v[42:45], v[122:125], v[194:197], v[42:45]
	v_mfma_f32_16x16x32_bf16 v[30:33], v[114:117], v[202:205], v[30:33]
	v_mfma_f32_16x16x32_bf16 v[26:29], v[122:125], v[202:205], v[26:29]
	v_mfma_f32_16x16x32_bf16 v[14:17], v[114:117], v[210:213], v[14:17]
	v_mfma_f32_16x16x32_bf16 v[10:13], v[122:125], v[210:213], v[10:13]
	v_mfma_f32_16x16x32_bf16 v[62:65], v[118:121], v[184:187], v[62:65]
	v_mfma_f32_16x16x32_bf16 v[58:61], v[134:137], v[184:187], v[58:61]
	v_mfma_f32_16x16x32_bf16 v[46:49], v[118:121], v[198:201], v[46:49]
	v_mfma_f32_16x16x32_bf16 v[42:45], v[134:137], v[198:201], v[42:45]
	v_mfma_f32_16x16x32_bf16 v[30:33], v[118:121], v[206:209], v[30:33]
	v_mfma_f32_16x16x32_bf16 v[26:29], v[134:137], v[206:209], v[26:29]
	v_mfma_f32_16x16x32_bf16 v[14:17], v[118:121], v[214:217], v[14:17]
	v_mfma_f32_16x16x32_bf16 v[10:13], v[134:137], v[214:217], v[10:13]
	s_setprio 0
	s_setprio 1
	v_mfma_f32_16x16x32_bf16 v[54:57], v[146:149], v[180:183], v[54:57]
	v_mfma_f32_16x16x32_bf16 v[50:53], v[172:175], v[180:183], v[50:53]
	v_mfma_f32_16x16x32_bf16 v[38:41], v[146:149], v[194:197], v[38:41]
	v_mfma_f32_16x16x32_bf16 v[34:37], v[172:175], v[194:197], v[34:37]
	v_mfma_f32_16x16x32_bf16 v[22:25], v[146:149], v[202:205], v[22:25]
	v_mfma_f32_16x16x32_bf16 v[18:21], v[172:175], v[202:205], v[18:21]
	v_mfma_f32_16x16x32_bf16 v[6:9], v[146:149], v[210:213], v[6:9]
	v_mfma_f32_16x16x32_bf16 v[2:5], v[172:175], v[210:213], v[2:5]
	v_mfma_f32_16x16x32_bf16 v[54:57], v[150:153], v[184:187], v[54:57]
	v_mfma_f32_16x16x32_bf16 v[50:53], v[176:179], v[184:187], v[50:53]
	v_mfma_f32_16x16x32_bf16 v[38:41], v[150:153], v[198:201], v[38:41]
	v_mfma_f32_16x16x32_bf16 v[34:37], v[176:179], v[198:201], v[34:37]
	v_mfma_f32_16x16x32_bf16 v[22:25], v[150:153], v[206:209], v[22:25]
	v_mfma_f32_16x16x32_bf16 v[18:21], v[176:179], v[206:209], v[18:21]
	v_mfma_f32_16x16x32_bf16 v[6:9], v[150:153], v[214:217], v[6:9]
	v_mfma_f32_16x16x32_bf16 v[2:5], v[176:179], v[214:217], v[2:5]
	s_setprio 0
	s_barrier
	s_add_i32 s45, s45, 2
	s_add_u32 s43, s43, 0x100
	s_addc_u32 s44, s44, 0
	s_cmp_gt_u32 s45, 41
	s_mov_b64 s[18:19], s[20:21]
	s_cbranch_scc0 .LBB0_966
